# scan8 body rescheduled: next-batch reads burst after y write, merged y writes, paired v reads
# speedup vs baseline: 1.0515x; 1.0116x over previous
; template <int KT>
; __device__ __forceinline__ void scan_block(const Ctx& C, const PV& P, int layer, int sq, int h, int d, int row0, unsigned char* smem) {
;     ...
;             for (int i = 0; i < CH; ++i) {
;                 f32x2 kk2[KT / 2], w2[KT / 2], b2[KT / 2], kd2[KT / 2], r2[KT / 2];
; #pragma unroll
;                 for (int u = 0; u < KT / 4; ++u) {
;                     kk2[2 * u] = (f32x2){nx[0][u][0], nx[0][u][1]}; kk2[2 * u + 1] = (f32x2){nx[0][u][2], nx[0][u][3]};
;                     w2[2 * u] = (f32x2){nx[1][u][0], nx[1][u][1]}; w2[2 * u + 1] = (f32x2){nx[1][u][2], nx[1][u][3]};
;                     b2[2 * u] = (f32x2){nx[2][u][0], nx[2][u][1]}; b2[2 * u + 1] = (f32x2){nx[2][u][2], nx[2][u][3]};
;                     kd2[2 * u] = (f32x2){nx[3][u][0], nx[3][u][1]}; kd2[2 * u + 1] = (f32x2){nx[3][u][2], nx[3][u][3]};
;                     r2[2 * u] = (f32x2){nx[4][u][0], nx[4][u][1]}; r2[2 * u + 1] = (f32x2){nx[4][u][2], nx[4][u][3]};
;                 }
;                 const float vv = nvv;
;                 if (i + 1 < CH) {
; #pragma unroll
;                     for (int u = 0; u < KT / 4; ++u)
; #pragma unroll
;                         for (int a5 = 0; a5 < 5; ++a5) nx[a5][u] = vp0[(i + 1) * 16 + a5 * CH * 16 + u];
;                     nvv = vbuf[(i + 1) * 64 + row];
;                 }
;                 f32x2 acc2 = s[0] * kk2[0];
; #pragma unroll
;                 for (int j = 1; j < KT / 2; ++j) acc2 = __builtin_elementwise_fma(s[j], kk2[j], acc2);
;                 float sa = acc2[0] + acc2[1];
;                 sa += dppf<0xB1>(sa); sa += dppf<0x4E>(sa); sa += dppf<0x141>(sa);
;                 if (TPR == 16) sa += dppf<0x140>(sa);
;                 sa = -sa;
;                 const f32x2 sa2 = (f32x2){sa, sa}, vv2 = (f32x2){vv, vv};
;                 f32x2 y2 = (f32x2){0.f, 0.f};
; #pragma unroll
;                 for (int j = 0; j < KT / 2; ++j) {
;                     s[j] = __builtin_elementwise_fma(s[j], w2[j], __builtin_elementwise_fma(sa2, b2[j], vv2 * kd2[j]));
;                     y2 = __builtin_elementwise_fma(s[j], r2[j], y2);
;                 }
;                 float y = y2[0] + y2[1];
;                 y += dppf<0xB1>(y); y += dppf<0x4E>(y);
;                 yv[i] = y;
;             }
;             if ((q & 3) == 0) {
; #pragma unroll
.LBB0_535:
	s_add_i32 s6, s16, 0xffff8000
	s_and_b32 s6, s6, 0x8000
	s_add_i32 s6, s6, 0
	s_cmpk_ge_u32 s27, 0x100
	s_cbranch_scc1 .Lsc8_skip
	v_add_u32_e32 v200, s6, v90
	v_lshl_add_u32 v201, v80, 2, s6
	v_add_u32_e32 v203, 0x80, v201
	v_and_b32_e32 v202, 4, v82
	v_add3_u32 v202, s6, v81, v202
	ds_read2st64_b32 v[186:187], v201 offset0:80 offset1:81
	ds_read2st64_b32 v[190:191], v203 offset0:80 offset1:81
	ds_read_b128 v[8:11], v200
	ds_read_b128 v[12:15], v200 offset:16
	ds_read_b128 v[32:35], v200 offset:12288
	ds_read_b128 v[36:39], v200 offset:12304
	ds_read_b128 v[24:27], v200 offset:8192
	ds_read_b128 v[28:31], v200 offset:8208
	ds_read_b128 v[16:19], v200 offset:4096
	ds_read_b128 v[20:23], v200 offset:4112
	ds_read_b128 v[48:51], v200 offset:16384
	ds_read_b128 v[52:55], v200 offset:16400
	s_waitcnt lgkmcnt(0)
	ds_read_b128 v[148:151], v200 offset:256
	ds_read_b128 v[152:155], v200 offset:272
	ds_read_b128 v[172:175], v200 offset:12544
	ds_read_b128 v[176:179], v200 offset:12560
	ds_read_b128 v[164:167], v200 offset:8448
	ds_read_b128 v[168:171], v200 offset:8464
	ds_read_b128 v[156:159], v200 offset:4352
	ds_read_b128 v[160:163], v200 offset:4368
	ds_read_b128 v[56:59], v200 offset:16640
	ds_read_b128 v[140:143], v200 offset:16656
	v_pk_mul_f32 v[104:105], v[0:1], v[8:9]
	v_pk_mul_f32 v[106:107], v[204:205], v[8:9]
	v_pk_fma_f32 v[104:105], v[2:3], v[10:11], v[104:105]
	v_pk_fma_f32 v[106:107], v[206:207], v[10:11], v[106:107]
	v_pk_fma_f32 v[104:105], v[4:5], v[12:13], v[104:105]
	v_pk_fma_f32 v[106:107], v[208:209], v[12:13], v[106:107]
	v_pk_fma_f32 v[104:105], v[6:7], v[14:15], v[104:105]
	v_pk_fma_f32 v[106:107], v[210:211], v[14:15], v[106:107]
	v_add_f32_e32 v108, v104, v105
	v_add_f32_e32 v110, v106, v107
	v_pk_mul_f32 v[112:113], v[32:33], v[186:187] op_sel_hi:[1,0]
	v_add_f32_dpp v108, v108, v108 quad_perm:[1,0,3,2] row_mask:0xf bank_mask:0xf bound_ctrl:1
	v_add_f32_dpp v110, v110, v110 quad_perm:[1,0,3,2] row_mask:0xf bank_mask:0xf bound_ctrl:1
	v_pk_mul_f32 v[120:121], v[32:33], v[190:191] op_sel_hi:[1,0]
	v_add_f32_dpp v108, v108, v108 quad_perm:[2,3,0,1] row_mask:0xf bank_mask:0xf bound_ctrl:1
	v_add_f32_dpp v110, v110, v110 quad_perm:[2,3,0,1] row_mask:0xf bank_mask:0xf bound_ctrl:1
	v_pk_mul_f32 v[114:115], v[34:35], v[186:187] op_sel_hi:[1,0]
	v_add_f32_dpp v108, v108, v108 row_half_mirror row_mask:0xf bank_mask:0xf bound_ctrl:1
	v_add_f32_dpp v110, v110, v110 row_half_mirror row_mask:0xf bank_mask:0xf bound_ctrl:1
	v_pk_mul_f32 v[122:123], v[34:35], v[190:191] op_sel_hi:[1,0]
	v_pk_mul_f32 v[116:117], v[36:37], v[186:187] op_sel_hi:[1,0]
	v_pk_mul_f32 v[124:125], v[36:37], v[190:191] op_sel_hi:[1,0]
	v_pk_mul_f32 v[118:119], v[38:39], v[186:187] op_sel_hi:[1,0]
	v_pk_mul_f32 v[126:127], v[38:39], v[190:191] op_sel_hi:[1,0]
	v_pk_fma_f32 v[112:113], v[108:109], v[24:25], v[112:113] op_sel_hi:[0,1,1] neg_lo:[1,0,0] neg_hi:[1,0,0]
	v_pk_fma_f32 v[120:121], v[110:111], v[24:25], v[120:121] op_sel_hi:[0,1,1] neg_lo:[1,0,0] neg_hi:[1,0,0]
	v_pk_fma_f32 v[114:115], v[108:109], v[26:27], v[114:115] op_sel_hi:[0,1,1] neg_lo:[1,0,0] neg_hi:[1,0,0]
	v_pk_fma_f32 v[122:123], v[110:111], v[26:27], v[122:123] op_sel_hi:[0,1,1] neg_lo:[1,0,0] neg_hi:[1,0,0]
	v_pk_fma_f32 v[116:117], v[108:109], v[28:29], v[116:117] op_sel_hi:[0,1,1] neg_lo:[1,0,0] neg_hi:[1,0,0]
	v_pk_fma_f32 v[124:125], v[110:111], v[28:29], v[124:125] op_sel_hi:[0,1,1] neg_lo:[1,0,0] neg_hi:[1,0,0]
	v_pk_fma_f32 v[118:119], v[108:109], v[30:31], v[118:119] op_sel_hi:[0,1,1] neg_lo:[1,0,0] neg_hi:[1,0,0]
	v_pk_fma_f32 v[126:127], v[110:111], v[30:31], v[126:127] op_sel_hi:[0,1,1] neg_lo:[1,0,0] neg_hi:[1,0,0]
	v_pk_fma_f32 v[0:1], v[0:1], v[16:17], v[112:113]
	v_pk_fma_f32 v[204:205], v[204:205], v[16:17], v[120:121]
	v_pk_fma_f32 v[2:3], v[2:3], v[18:19], v[114:115]
	v_pk_fma_f32 v[206:207], v[206:207], v[18:19], v[122:123]
	v_pk_fma_f32 v[4:5], v[4:5], v[20:21], v[116:117]
	v_pk_fma_f32 v[208:209], v[208:209], v[20:21], v[124:125]
	v_pk_fma_f32 v[6:7], v[6:7], v[22:23], v[118:119]
	v_pk_fma_f32 v[210:211], v[210:211], v[22:23], v[126:127]
	v_pk_fma_f32 v[128:129], v[0:1], v[48:49], 0 op_sel_hi:[1,1,0]
	v_pk_fma_f32 v[130:131], v[204:205], v[48:49], 0 op_sel_hi:[1,1,0]
	v_pk_fma_f32 v[128:129], v[2:3], v[50:51], v[128:129]
	v_pk_fma_f32 v[130:131], v[206:207], v[50:51], v[130:131]
	v_pk_fma_f32 v[128:129], v[4:5], v[52:53], v[128:129]
	v_pk_fma_f32 v[130:131], v[208:209], v[52:53], v[130:131]
	v_pk_fma_f32 v[128:129], v[6:7], v[54:55], v[128:129]
	v_pk_fma_f32 v[130:131], v[210:211], v[54:55], v[130:131]
	v_add_f32_e32 v102, v128, v129
	v_add_f32_e32 v103, v130, v131
	s_waitcnt lgkmcnt(0)
; template <int KT>
; __device__ __forceinline__ void scan_block(const Ctx& C, const PV& P, int layer, int sq, int h, int d, int row0, unsigned char* smem) {
;     ...
;             for (int i = 0; i < CH; ++i) {
;                 f32x2 kk2[KT / 2], w2[KT / 2], b2[KT / 2], kd2[KT / 2], r2[KT / 2];
; #pragma unroll
;                 for (int u = 0; u < KT / 4; ++u) {
;                     kk2[2 * u] = (f32x2){nx[0][u][0], nx[0][u][1]}; kk2[2 * u + 1] = (f32x2){nx[0][u][2], nx[0][u][3]};
;                     w2[2 * u] = (f32x2){nx[1][u][0], nx[1][u][1]}; w2[2 * u + 1] = (f32x2){nx[1][u][2], nx[1][u][3]};
;                     b2[2 * u] = (f32x2){nx[2][u][0], nx[2][u][1]}; b2[2 * u + 1] = (f32x2){nx[2][u][2], nx[2][u][3]};
;                     kd2[2 * u] = (f32x2){nx[3][u][0], nx[3][u][1]}; kd2[2 * u + 1] = (f32x2){nx[3][u][2], nx[3][u][3]};
;                     r2[2 * u] = (f32x2){nx[4][u][0], nx[4][u][1]}; r2[2 * u + 1] = (f32x2){nx[4][u][2], nx[4][u][3]};
;                 }
;                 const float vv = nvv;
;                 if (i + 1 < CH) {
; #pragma unroll
;                     for (int u = 0; u < KT / 4; ++u)
; #pragma unroll
;                         for (int a5 = 0; a5 < 5; ++a5) nx[a5][u] = vp0[(i + 1) * 16 + a5 * CH * 16 + u];
;                     nvv = vbuf[(i + 1) * 64 + row];
;                 }
;                 f32x2 acc2 = s[0] * kk2[0];
; #pragma unroll
;                 for (int j = 1; j < KT / 2; ++j) acc2 = __builtin_elementwise_fma(s[j], kk2[j], acc2);
;                 float sa = acc2[0] + acc2[1];
;                 sa += dppf<0xB1>(sa); sa += dppf<0x4E>(sa); sa += dppf<0x141>(sa);
;                 if (TPR == 16) sa += dppf<0x140>(sa);
;                 sa = -sa;
;                 const f32x2 sa2 = (f32x2){sa, sa}, vv2 = (f32x2){vv, vv};
;                 f32x2 y2 = (f32x2){0.f, 0.f};
; #pragma unroll
;                 for (int j = 0; j < KT / 2; ++j) {
;                     s[j] = __builtin_elementwise_fma(s[j], w2[j], __builtin_elementwise_fma(sa2, b2[j], vv2 * kd2[j]));
;                     y2 = __builtin_elementwise_fma(s[j], r2[j], y2);
;                 }
;                 float y = y2[0] + y2[1];
;                 y += dppf<0xB1>(y); y += dppf<0x4E>(y);
;                 yv[i] = y;
;             }
;             if ((q & 3) == 0) {
; #pragma unroll
	v_add_f32_dpp v102, v102, v102 quad_perm:[1,0,3,2] row_mask:0xf bank_mask:0xf bound_ctrl:1
	v_add_f32_dpp v103, v103, v103 quad_perm:[1,0,3,2] row_mask:0xf bank_mask:0xf bound_ctrl:1
	ds_read2st64_b32 v[188:189], v201 offset0:82 offset1:83
	v_add_f32_dpp v102, v102, v102 quad_perm:[2,3,0,1] row_mask:0xf bank_mask:0xf bound_ctrl:1
	v_add_f32_dpp v103, v103, v103 quad_perm:[2,3,0,1] row_mask:0xf bank_mask:0xf bound_ctrl:1
	ds_write2st64_b32 v202, v102, v103 offset0:96 offset1:97
	ds_read2st64_b32 v[192:193], v203 offset0:82 offset1:83
	ds_read_b128 v[8:11], v200 offset:512
	ds_read_b128 v[12:15], v200 offset:528
	ds_read_b128 v[32:35], v200 offset:12800
	ds_read_b128 v[36:39], v200 offset:12816
	ds_read_b128 v[24:27], v200 offset:8704
	ds_read_b128 v[28:31], v200 offset:8720
	ds_read_b128 v[16:19], v200 offset:4608
	ds_read_b128 v[20:23], v200 offset:4624
	ds_read_b128 v[48:51], v200 offset:16896
	ds_read_b128 v[52:55], v200 offset:16912
	v_pk_mul_f32 v[104:105], v[0:1], v[148:149]
	v_pk_mul_f32 v[106:107], v[204:205], v[148:149]
	v_pk_fma_f32 v[104:105], v[2:3], v[150:151], v[104:105]
	v_pk_fma_f32 v[106:107], v[206:207], v[150:151], v[106:107]
	v_pk_fma_f32 v[104:105], v[4:5], v[152:153], v[104:105]
	v_pk_fma_f32 v[106:107], v[208:209], v[152:153], v[106:107]
	v_pk_fma_f32 v[104:105], v[6:7], v[154:155], v[104:105]
	v_pk_fma_f32 v[106:107], v[210:211], v[154:155], v[106:107]
	v_add_f32_e32 v108, v104, v105
	v_add_f32_e32 v110, v106, v107
	v_pk_mul_f32 v[112:113], v[172:173], v[186:187] op_sel:[0,1] op_sel_hi:[1,1]
	v_add_f32_dpp v108, v108, v108 quad_perm:[1,0,3,2] row_mask:0xf bank_mask:0xf bound_ctrl:1
	v_add_f32_dpp v110, v110, v110 quad_perm:[1,0,3,2] row_mask:0xf bank_mask:0xf bound_ctrl:1
	v_pk_mul_f32 v[120:121], v[172:173], v[190:191] op_sel:[0,1] op_sel_hi:[1,1]
	v_add_f32_dpp v108, v108, v108 quad_perm:[2,3,0,1] row_mask:0xf bank_mask:0xf bound_ctrl:1
	v_add_f32_dpp v110, v110, v110 quad_perm:[2,3,0,1] row_mask:0xf bank_mask:0xf bound_ctrl:1
	v_pk_mul_f32 v[114:115], v[174:175], v[186:187] op_sel:[0,1] op_sel_hi:[1,1]
	v_add_f32_dpp v108, v108, v108 row_half_mirror row_mask:0xf bank_mask:0xf bound_ctrl:1
	v_add_f32_dpp v110, v110, v110 row_half_mirror row_mask:0xf bank_mask:0xf bound_ctrl:1
	v_pk_mul_f32 v[122:123], v[174:175], v[190:191] op_sel:[0,1] op_sel_hi:[1,1]
	v_pk_mul_f32 v[116:117], v[176:177], v[186:187] op_sel:[0,1] op_sel_hi:[1,1]
	v_pk_mul_f32 v[124:125], v[176:177], v[190:191] op_sel:[0,1] op_sel_hi:[1,1]
	v_pk_mul_f32 v[118:119], v[178:179], v[186:187] op_sel:[0,1] op_sel_hi:[1,1]
	v_pk_mul_f32 v[126:127], v[178:179], v[190:191] op_sel:[0,1] op_sel_hi:[1,1]
	v_pk_fma_f32 v[112:113], v[108:109], v[164:165], v[112:113] op_sel_hi:[0,1,1] neg_lo:[1,0,0] neg_hi:[1,0,0]
	v_pk_fma_f32 v[120:121], v[110:111], v[164:165], v[120:121] op_sel_hi:[0,1,1] neg_lo:[1,0,0] neg_hi:[1,0,0]
	v_pk_fma_f32 v[114:115], v[108:109], v[166:167], v[114:115] op_sel_hi:[0,1,1] neg_lo:[1,0,0] neg_hi:[1,0,0]
	v_pk_fma_f32 v[122:123], v[110:111], v[166:167], v[122:123] op_sel_hi:[0,1,1] neg_lo:[1,0,0] neg_hi:[1,0,0]
	v_pk_fma_f32 v[116:117], v[108:109], v[168:169], v[116:117] op_sel_hi:[0,1,1] neg_lo:[1,0,0] neg_hi:[1,0,0]
	v_pk_fma_f32 v[124:125], v[110:111], v[168:169], v[124:125] op_sel_hi:[0,1,1] neg_lo:[1,0,0] neg_hi:[1,0,0]
	v_pk_fma_f32 v[118:119], v[108:109], v[170:171], v[118:119] op_sel_hi:[0,1,1] neg_lo:[1,0,0] neg_hi:[1,0,0]
	v_pk_fma_f32 v[126:127], v[110:111], v[170:171], v[126:127] op_sel_hi:[0,1,1] neg_lo:[1,0,0] neg_hi:[1,0,0]
	v_pk_fma_f32 v[0:1], v[0:1], v[156:157], v[112:113]
	v_pk_fma_f32 v[204:205], v[204:205], v[156:157], v[120:121]
	v_pk_fma_f32 v[2:3], v[2:3], v[158:159], v[114:115]
	v_pk_fma_f32 v[206:207], v[206:207], v[158:159], v[122:123]
	v_pk_fma_f32 v[4:5], v[4:5], v[160:161], v[116:117]
	v_pk_fma_f32 v[208:209], v[208:209], v[160:161], v[124:125]
	v_pk_fma_f32 v[6:7], v[6:7], v[162:163], v[118:119]
	v_pk_fma_f32 v[210:211], v[210:211], v[162:163], v[126:127]
	v_pk_fma_f32 v[128:129], v[0:1], v[56:57], 0 op_sel_hi:[1,1,0]
	v_pk_fma_f32 v[130:131], v[204:205], v[56:57], 0 op_sel_hi:[1,1,0]
	v_pk_fma_f32 v[128:129], v[2:3], v[58:59], v[128:129]
	v_pk_fma_f32 v[130:131], v[206:207], v[58:59], v[130:131]
	v_pk_fma_f32 v[128:129], v[4:5], v[140:141], v[128:129]
	v_pk_fma_f32 v[130:131], v[208:209], v[140:141], v[130:131]
	v_pk_fma_f32 v[128:129], v[6:7], v[142:143], v[128:129]
	v_pk_fma_f32 v[130:131], v[210:211], v[142:143], v[130:131]
	v_add_f32_e32 v102, v128, v129
	v_add_f32_e32 v103, v130, v131
	s_waitcnt lgkmcnt(0)
; template <int KT>
; __device__ __forceinline__ void scan_block(const Ctx& C, const PV& P, int layer, int sq, int h, int d, int row0, unsigned char* smem) {
;     ...
;             for (int i = 0; i < CH; ++i) {
;                 f32x2 kk2[KT / 2], w2[KT / 2], b2[KT / 2], kd2[KT / 2], r2[KT / 2];
; #pragma unroll
;                 for (int u = 0; u < KT / 4; ++u) {
;                     kk2[2 * u] = (f32x2){nx[0][u][0], nx[0][u][1]}; kk2[2 * u + 1] = (f32x2){nx[0][u][2], nx[0][u][3]};
;                     w2[2 * u] = (f32x2){nx[1][u][0], nx[1][u][1]}; w2[2 * u + 1] = (f32x2){nx[1][u][2], nx[1][u][3]};
;                     b2[2 * u] = (f32x2){nx[2][u][0], nx[2][u][1]}; b2[2 * u + 1] = (f32x2){nx[2][u][2], nx[2][u][3]};
;                     kd2[2 * u] = (f32x2){nx[3][u][0], nx[3][u][1]}; kd2[2 * u + 1] = (f32x2){nx[3][u][2], nx[3][u][3]};
;                     r2[2 * u] = (f32x2){nx[4][u][0], nx[4][u][1]}; r2[2 * u + 1] = (f32x2){nx[4][u][2], nx[4][u][3]};
;                 }
;                 const float vv = nvv;
;                 if (i + 1 < CH) {
; #pragma unroll
;                     for (int u = 0; u < KT / 4; ++u)
; #pragma unroll
;                         for (int a5 = 0; a5 < 5; ++a5) nx[a5][u] = vp0[(i + 1) * 16 + a5 * CH * 16 + u];
;                     nvv = vbuf[(i + 1) * 64 + row];
;                 }
;                 f32x2 acc2 = s[0] * kk2[0];
; #pragma unroll
;                 for (int j = 1; j < KT / 2; ++j) acc2 = __builtin_elementwise_fma(s[j], kk2[j], acc2);
;                 float sa = acc2[0] + acc2[1];
;                 sa += dppf<0xB1>(sa); sa += dppf<0x4E>(sa); sa += dppf<0x141>(sa);
;                 if (TPR == 16) sa += dppf<0x140>(sa);
;                 sa = -sa;
;                 const f32x2 sa2 = (f32x2){sa, sa}, vv2 = (f32x2){vv, vv};
;                 f32x2 y2 = (f32x2){0.f, 0.f};
; #pragma unroll
;                 for (int j = 0; j < KT / 2; ++j) {
;                     s[j] = __builtin_elementwise_fma(s[j], w2[j], __builtin_elementwise_fma(sa2, b2[j], vv2 * kd2[j]));
;                     y2 = __builtin_elementwise_fma(s[j], r2[j], y2);
;                 }
;                 float y = y2[0] + y2[1];
;                 y += dppf<0xB1>(y); y += dppf<0x4E>(y);
;                 yv[i] = y;
;             }
;             if ((q & 3) == 0) {
; #pragma unroll
	v_add_f32_dpp v102, v102, v102 quad_perm:[1,0,3,2] row_mask:0xf bank_mask:0xf bound_ctrl:1
	v_add_f32_dpp v103, v103, v103 quad_perm:[1,0,3,2] row_mask:0xf bank_mask:0xf bound_ctrl:1
	ds_read_b128 v[148:151], v200 offset:768
	v_add_f32_dpp v102, v102, v102 quad_perm:[2,3,0,1] row_mask:0xf bank_mask:0xf bound_ctrl:1
	v_add_f32_dpp v103, v103, v103 quad_perm:[2,3,0,1] row_mask:0xf bank_mask:0xf bound_ctrl:1
	ds_write2st64_b32 v202, v102, v103 offset0:98 offset1:99
	ds_read_b128 v[152:155], v200 offset:784
	ds_read_b128 v[172:175], v200 offset:13056
	ds_read_b128 v[176:179], v200 offset:13072
	ds_read_b128 v[164:167], v200 offset:8960
	ds_read_b128 v[168:171], v200 offset:8976
	ds_read_b128 v[156:159], v200 offset:4864
	ds_read_b128 v[160:163], v200 offset:4880
	ds_read_b128 v[56:59], v200 offset:17152
	ds_read_b128 v[140:143], v200 offset:17168
	v_pk_mul_f32 v[104:105], v[0:1], v[8:9]
	v_pk_mul_f32 v[106:107], v[204:205], v[8:9]
	v_pk_fma_f32 v[104:105], v[2:3], v[10:11], v[104:105]
	v_pk_fma_f32 v[106:107], v[206:207], v[10:11], v[106:107]
	v_pk_fma_f32 v[104:105], v[4:5], v[12:13], v[104:105]
	v_pk_fma_f32 v[106:107], v[208:209], v[12:13], v[106:107]
	v_pk_fma_f32 v[104:105], v[6:7], v[14:15], v[104:105]
	v_pk_fma_f32 v[106:107], v[210:211], v[14:15], v[106:107]
	v_add_f32_e32 v108, v104, v105
	v_add_f32_e32 v110, v106, v107
	v_pk_mul_f32 v[112:113], v[32:33], v[188:189] op_sel_hi:[1,0]
	v_add_f32_dpp v108, v108, v108 quad_perm:[1,0,3,2] row_mask:0xf bank_mask:0xf bound_ctrl:1
	v_add_f32_dpp v110, v110, v110 quad_perm:[1,0,3,2] row_mask:0xf bank_mask:0xf bound_ctrl:1
	v_pk_mul_f32 v[120:121], v[32:33], v[192:193] op_sel_hi:[1,0]
	v_add_f32_dpp v108, v108, v108 quad_perm:[2,3,0,1] row_mask:0xf bank_mask:0xf bound_ctrl:1
	v_add_f32_dpp v110, v110, v110 quad_perm:[2,3,0,1] row_mask:0xf bank_mask:0xf bound_ctrl:1
	v_pk_mul_f32 v[114:115], v[34:35], v[188:189] op_sel_hi:[1,0]
	v_add_f32_dpp v108, v108, v108 row_half_mirror row_mask:0xf bank_mask:0xf bound_ctrl:1
	v_add_f32_dpp v110, v110, v110 row_half_mirror row_mask:0xf bank_mask:0xf bound_ctrl:1
	v_pk_mul_f32 v[122:123], v[34:35], v[192:193] op_sel_hi:[1,0]
	v_pk_mul_f32 v[116:117], v[36:37], v[188:189] op_sel_hi:[1,0]
	v_pk_mul_f32 v[124:125], v[36:37], v[192:193] op_sel_hi:[1,0]
	v_pk_mul_f32 v[118:119], v[38:39], v[188:189] op_sel_hi:[1,0]
	v_pk_mul_f32 v[126:127], v[38:39], v[192:193] op_sel_hi:[1,0]
	v_pk_fma_f32 v[112:113], v[108:109], v[24:25], v[112:113] op_sel_hi:[0,1,1] neg_lo:[1,0,0] neg_hi:[1,0,0]
	v_pk_fma_f32 v[120:121], v[110:111], v[24:25], v[120:121] op_sel_hi:[0,1,1] neg_lo:[1,0,0] neg_hi:[1,0,0]
	v_pk_fma_f32 v[114:115], v[108:109], v[26:27], v[114:115] op_sel_hi:[0,1,1] neg_lo:[1,0,0] neg_hi:[1,0,0]
	v_pk_fma_f32 v[122:123], v[110:111], v[26:27], v[122:123] op_sel_hi:[0,1,1] neg_lo:[1,0,0] neg_hi:[1,0,0]
	v_pk_fma_f32 v[116:117], v[108:109], v[28:29], v[116:117] op_sel_hi:[0,1,1] neg_lo:[1,0,0] neg_hi:[1,0,0]
	v_pk_fma_f32 v[124:125], v[110:111], v[28:29], v[124:125] op_sel_hi:[0,1,1] neg_lo:[1,0,0] neg_hi:[1,0,0]
	v_pk_fma_f32 v[118:119], v[108:109], v[30:31], v[118:119] op_sel_hi:[0,1,1] neg_lo:[1,0,0] neg_hi:[1,0,0]
	v_pk_fma_f32 v[126:127], v[110:111], v[30:31], v[126:127] op_sel_hi:[0,1,1] neg_lo:[1,0,0] neg_hi:[1,0,0]
	v_pk_fma_f32 v[0:1], v[0:1], v[16:17], v[112:113]
	v_pk_fma_f32 v[204:205], v[204:205], v[16:17], v[120:121]
	v_pk_fma_f32 v[2:3], v[2:3], v[18:19], v[114:115]
	v_pk_fma_f32 v[206:207], v[206:207], v[18:19], v[122:123]
	v_pk_fma_f32 v[4:5], v[4:5], v[20:21], v[116:117]
	v_pk_fma_f32 v[208:209], v[208:209], v[20:21], v[124:125]
	v_pk_fma_f32 v[6:7], v[6:7], v[22:23], v[118:119]
	v_pk_fma_f32 v[210:211], v[210:211], v[22:23], v[126:127]
	v_pk_fma_f32 v[128:129], v[0:1], v[48:49], 0 op_sel_hi:[1,1,0]
	v_pk_fma_f32 v[130:131], v[204:205], v[48:49], 0 op_sel_hi:[1,1,0]
	v_pk_fma_f32 v[128:129], v[2:3], v[50:51], v[128:129]
	v_pk_fma_f32 v[130:131], v[206:207], v[50:51], v[130:131]
	v_pk_fma_f32 v[128:129], v[4:5], v[52:53], v[128:129]
	v_pk_fma_f32 v[130:131], v[208:209], v[52:53], v[130:131]
	v_pk_fma_f32 v[128:129], v[6:7], v[54:55], v[128:129]
	v_pk_fma_f32 v[130:131], v[210:211], v[54:55], v[130:131]
	v_add_f32_e32 v102, v128, v129
	v_add_f32_e32 v103, v130, v131
	s_waitcnt lgkmcnt(0)
; template <int KT>
; __device__ __forceinline__ void scan_block(const Ctx& C, const PV& P, int layer, int sq, int h, int d, int row0, unsigned char* smem) {
;     ...
;             for (int i = 0; i < CH; ++i) {
;                 f32x2 kk2[KT / 2], w2[KT / 2], b2[KT / 2], kd2[KT / 2], r2[KT / 2];
; #pragma unroll
;                 for (int u = 0; u < KT / 4; ++u) {
;                     kk2[2 * u] = (f32x2){nx[0][u][0], nx[0][u][1]}; kk2[2 * u + 1] = (f32x2){nx[0][u][2], nx[0][u][3]};
;                     w2[2 * u] = (f32x2){nx[1][u][0], nx[1][u][1]}; w2[2 * u + 1] = (f32x2){nx[1][u][2], nx[1][u][3]};
;                     b2[2 * u] = (f32x2){nx[2][u][0], nx[2][u][1]}; b2[2 * u + 1] = (f32x2){nx[2][u][2], nx[2][u][3]};
;                     kd2[2 * u] = (f32x2){nx[3][u][0], nx[3][u][1]}; kd2[2 * u + 1] = (f32x2){nx[3][u][2], nx[3][u][3]};
;                     r2[2 * u] = (f32x2){nx[4][u][0], nx[4][u][1]}; r2[2 * u + 1] = (f32x2){nx[4][u][2], nx[4][u][3]};
;                 }
;                 const float vv = nvv;
;                 if (i + 1 < CH) {
; #pragma unroll
;                     for (int u = 0; u < KT / 4; ++u)
; #pragma unroll
;                         for (int a5 = 0; a5 < 5; ++a5) nx[a5][u] = vp0[(i + 1) * 16 + a5 * CH * 16 + u];
;                     nvv = vbuf[(i + 1) * 64 + row];
;                 }
;                 f32x2 acc2 = s[0] * kk2[0];
; #pragma unroll
;                 for (int j = 1; j < KT / 2; ++j) acc2 = __builtin_elementwise_fma(s[j], kk2[j], acc2);
;                 float sa = acc2[0] + acc2[1];
;                 sa += dppf<0xB1>(sa); sa += dppf<0x4E>(sa); sa += dppf<0x141>(sa);
;                 if (TPR == 16) sa += dppf<0x140>(sa);
;                 sa = -sa;
;                 const f32x2 sa2 = (f32x2){sa, sa}, vv2 = (f32x2){vv, vv};
;                 f32x2 y2 = (f32x2){0.f, 0.f};
; #pragma unroll
;                 for (int j = 0; j < KT / 2; ++j) {
;                     s[j] = __builtin_elementwise_fma(s[j], w2[j], __builtin_elementwise_fma(sa2, b2[j], vv2 * kd2[j]));
;                     y2 = __builtin_elementwise_fma(s[j], r2[j], y2);
;                 }
;                 float y = y2[0] + y2[1];
;                 y += dppf<0xB1>(y); y += dppf<0x4E>(y);
;                 yv[i] = y;
;             }
;             if ((q & 3) == 0) {
; #pragma unroll
	v_add_f32_dpp v102, v102, v102 quad_perm:[1,0,3,2] row_mask:0xf bank_mask:0xf bound_ctrl:1
	v_add_f32_dpp v103, v103, v103 quad_perm:[1,0,3,2] row_mask:0xf bank_mask:0xf bound_ctrl:1
	ds_read2st64_b32 v[186:187], v201 offset0:84 offset1:85
	v_add_f32_dpp v102, v102, v102 quad_perm:[2,3,0,1] row_mask:0xf bank_mask:0xf bound_ctrl:1
	v_add_f32_dpp v103, v103, v103 quad_perm:[2,3,0,1] row_mask:0xf bank_mask:0xf bound_ctrl:1
	ds_write2st64_b32 v202, v102, v103 offset0:100 offset1:101
	ds_read2st64_b32 v[190:191], v203 offset0:84 offset1:85
	ds_read_b128 v[8:11], v200 offset:1024
	ds_read_b128 v[12:15], v200 offset:1040
	ds_read_b128 v[32:35], v200 offset:13312
	ds_read_b128 v[36:39], v200 offset:13328
	ds_read_b128 v[24:27], v200 offset:9216
	ds_read_b128 v[28:31], v200 offset:9232
	ds_read_b128 v[16:19], v200 offset:5120
	ds_read_b128 v[20:23], v200 offset:5136
	ds_read_b128 v[48:51], v200 offset:17408
	ds_read_b128 v[52:55], v200 offset:17424
	v_pk_mul_f32 v[104:105], v[0:1], v[148:149]
	v_pk_mul_f32 v[106:107], v[204:205], v[148:149]
	v_pk_fma_f32 v[104:105], v[2:3], v[150:151], v[104:105]
	v_pk_fma_f32 v[106:107], v[206:207], v[150:151], v[106:107]
	v_pk_fma_f32 v[104:105], v[4:5], v[152:153], v[104:105]
	v_pk_fma_f32 v[106:107], v[208:209], v[152:153], v[106:107]
	v_pk_fma_f32 v[104:105], v[6:7], v[154:155], v[104:105]
	v_pk_fma_f32 v[106:107], v[210:211], v[154:155], v[106:107]
	v_add_f32_e32 v108, v104, v105
	v_add_f32_e32 v110, v106, v107
	v_pk_mul_f32 v[112:113], v[172:173], v[188:189] op_sel:[0,1] op_sel_hi:[1,1]
	v_add_f32_dpp v108, v108, v108 quad_perm:[1,0,3,2] row_mask:0xf bank_mask:0xf bound_ctrl:1
	v_add_f32_dpp v110, v110, v110 quad_perm:[1,0,3,2] row_mask:0xf bank_mask:0xf bound_ctrl:1
	v_pk_mul_f32 v[120:121], v[172:173], v[192:193] op_sel:[0,1] op_sel_hi:[1,1]
	v_add_f32_dpp v108, v108, v108 quad_perm:[2,3,0,1] row_mask:0xf bank_mask:0xf bound_ctrl:1
	v_add_f32_dpp v110, v110, v110 quad_perm:[2,3,0,1] row_mask:0xf bank_mask:0xf bound_ctrl:1
	v_pk_mul_f32 v[114:115], v[174:175], v[188:189] op_sel:[0,1] op_sel_hi:[1,1]
	v_add_f32_dpp v108, v108, v108 row_half_mirror row_mask:0xf bank_mask:0xf bound_ctrl:1
	v_add_f32_dpp v110, v110, v110 row_half_mirror row_mask:0xf bank_mask:0xf bound_ctrl:1
	v_pk_mul_f32 v[122:123], v[174:175], v[192:193] op_sel:[0,1] op_sel_hi:[1,1]
	v_pk_mul_f32 v[116:117], v[176:177], v[188:189] op_sel:[0,1] op_sel_hi:[1,1]
	v_pk_mul_f32 v[124:125], v[176:177], v[192:193] op_sel:[0,1] op_sel_hi:[1,1]
	v_pk_mul_f32 v[118:119], v[178:179], v[188:189] op_sel:[0,1] op_sel_hi:[1,1]
	v_pk_mul_f32 v[126:127], v[178:179], v[192:193] op_sel:[0,1] op_sel_hi:[1,1]
	v_pk_fma_f32 v[112:113], v[108:109], v[164:165], v[112:113] op_sel_hi:[0,1,1] neg_lo:[1,0,0] neg_hi:[1,0,0]
	v_pk_fma_f32 v[120:121], v[110:111], v[164:165], v[120:121] op_sel_hi:[0,1,1] neg_lo:[1,0,0] neg_hi:[1,0,0]
	v_pk_fma_f32 v[114:115], v[108:109], v[166:167], v[114:115] op_sel_hi:[0,1,1] neg_lo:[1,0,0] neg_hi:[1,0,0]
	v_pk_fma_f32 v[122:123], v[110:111], v[166:167], v[122:123] op_sel_hi:[0,1,1] neg_lo:[1,0,0] neg_hi:[1,0,0]
	v_pk_fma_f32 v[116:117], v[108:109], v[168:169], v[116:117] op_sel_hi:[0,1,1] neg_lo:[1,0,0] neg_hi:[1,0,0]
	v_pk_fma_f32 v[124:125], v[110:111], v[168:169], v[124:125] op_sel_hi:[0,1,1] neg_lo:[1,0,0] neg_hi:[1,0,0]
	v_pk_fma_f32 v[118:119], v[108:109], v[170:171], v[118:119] op_sel_hi:[0,1,1] neg_lo:[1,0,0] neg_hi:[1,0,0]
	v_pk_fma_f32 v[126:127], v[110:111], v[170:171], v[126:127] op_sel_hi:[0,1,1] neg_lo:[1,0,0] neg_hi:[1,0,0]
	v_pk_fma_f32 v[0:1], v[0:1], v[156:157], v[112:113]
	v_pk_fma_f32 v[204:205], v[204:205], v[156:157], v[120:121]
	v_pk_fma_f32 v[2:3], v[2:3], v[158:159], v[114:115]
	v_pk_fma_f32 v[206:207], v[206:207], v[158:159], v[122:123]
	v_pk_fma_f32 v[4:5], v[4:5], v[160:161], v[116:117]
	v_pk_fma_f32 v[208:209], v[208:209], v[160:161], v[124:125]
	v_pk_fma_f32 v[6:7], v[6:7], v[162:163], v[118:119]
	v_pk_fma_f32 v[210:211], v[210:211], v[162:163], v[126:127]
	v_pk_fma_f32 v[128:129], v[0:1], v[56:57], 0 op_sel_hi:[1,1,0]
	v_pk_fma_f32 v[130:131], v[204:205], v[56:57], 0 op_sel_hi:[1,1,0]
	v_pk_fma_f32 v[128:129], v[2:3], v[58:59], v[128:129]
	v_pk_fma_f32 v[130:131], v[206:207], v[58:59], v[130:131]
	v_pk_fma_f32 v[128:129], v[4:5], v[140:141], v[128:129]
	v_pk_fma_f32 v[130:131], v[208:209], v[140:141], v[130:131]
	v_pk_fma_f32 v[128:129], v[6:7], v[142:143], v[128:129]
	v_pk_fma_f32 v[130:131], v[210:211], v[142:143], v[130:131]
	v_add_f32_e32 v102, v128, v129
	v_add_f32_e32 v103, v130, v131
	s_waitcnt lgkmcnt(0)
; template <int KT>
; __device__ __forceinline__ void scan_block(const Ctx& C, const PV& P, int layer, int sq, int h, int d, int row0, unsigned char* smem) {
;     ...
;             for (int i = 0; i < CH; ++i) {
;                 f32x2 kk2[KT / 2], w2[KT / 2], b2[KT / 2], kd2[KT / 2], r2[KT / 2];
; #pragma unroll
;                 for (int u = 0; u < KT / 4; ++u) {
;                     kk2[2 * u] = (f32x2){nx[0][u][0], nx[0][u][1]}; kk2[2 * u + 1] = (f32x2){nx[0][u][2], nx[0][u][3]};
;                     w2[2 * u] = (f32x2){nx[1][u][0], nx[1][u][1]}; w2[2 * u + 1] = (f32x2){nx[1][u][2], nx[1][u][3]};
;                     b2[2 * u] = (f32x2){nx[2][u][0], nx[2][u][1]}; b2[2 * u + 1] = (f32x2){nx[2][u][2], nx[2][u][3]};
;                     kd2[2 * u] = (f32x2){nx[3][u][0], nx[3][u][1]}; kd2[2 * u + 1] = (f32x2){nx[3][u][2], nx[3][u][3]};
;                     r2[2 * u] = (f32x2){nx[4][u][0], nx[4][u][1]}; r2[2 * u + 1] = (f32x2){nx[4][u][2], nx[4][u][3]};
;                 }
;                 const float vv = nvv;
;                 if (i + 1 < CH) {
; #pragma unroll
;                     for (int u = 0; u < KT / 4; ++u)
; #pragma unroll
;                         for (int a5 = 0; a5 < 5; ++a5) nx[a5][u] = vp0[(i + 1) * 16 + a5 * CH * 16 + u];
;                     nvv = vbuf[(i + 1) * 64 + row];
;                 }
;                 f32x2 acc2 = s[0] * kk2[0];
; #pragma unroll
;                 for (int j = 1; j < KT / 2; ++j) acc2 = __builtin_elementwise_fma(s[j], kk2[j], acc2);
;                 float sa = acc2[0] + acc2[1];
;                 sa += dppf<0xB1>(sa); sa += dppf<0x4E>(sa); sa += dppf<0x141>(sa);
;                 if (TPR == 16) sa += dppf<0x140>(sa);
;                 sa = -sa;
;                 const f32x2 sa2 = (f32x2){sa, sa}, vv2 = (f32x2){vv, vv};
;                 f32x2 y2 = (f32x2){0.f, 0.f};
; #pragma unroll
;                 for (int j = 0; j < KT / 2; ++j) {
;                     s[j] = __builtin_elementwise_fma(s[j], w2[j], __builtin_elementwise_fma(sa2, b2[j], vv2 * kd2[j]));
;                     y2 = __builtin_elementwise_fma(s[j], r2[j], y2);
;                 }
;                 float y = y2[0] + y2[1];
;                 y += dppf<0xB1>(y); y += dppf<0x4E>(y);
;                 yv[i] = y;
;             }
;             if ((q & 3) == 0) {
; #pragma unroll
	v_add_f32_dpp v102, v102, v102 quad_perm:[1,0,3,2] row_mask:0xf bank_mask:0xf bound_ctrl:1
	v_add_f32_dpp v103, v103, v103 quad_perm:[1,0,3,2] row_mask:0xf bank_mask:0xf bound_ctrl:1
	ds_read_b128 v[148:151], v200 offset:1280
	v_add_f32_dpp v102, v102, v102 quad_perm:[2,3,0,1] row_mask:0xf bank_mask:0xf bound_ctrl:1
	v_add_f32_dpp v103, v103, v103 quad_perm:[2,3,0,1] row_mask:0xf bank_mask:0xf bound_ctrl:1
	ds_write2st64_b32 v202, v102, v103 offset0:102 offset1:103
	ds_read_b128 v[152:155], v200 offset:1296
	ds_read_b128 v[172:175], v200 offset:13568
	ds_read_b128 v[176:179], v200 offset:13584
	ds_read_b128 v[164:167], v200 offset:9472
	ds_read_b128 v[168:171], v200 offset:9488
	ds_read_b128 v[156:159], v200 offset:5376
	ds_read_b128 v[160:163], v200 offset:5392
	ds_read_b128 v[56:59], v200 offset:17664
	ds_read_b128 v[140:143], v200 offset:17680
	v_pk_mul_f32 v[104:105], v[0:1], v[8:9]
	v_pk_mul_f32 v[106:107], v[204:205], v[8:9]
	v_pk_fma_f32 v[104:105], v[2:3], v[10:11], v[104:105]
	v_pk_fma_f32 v[106:107], v[206:207], v[10:11], v[106:107]
	v_pk_fma_f32 v[104:105], v[4:5], v[12:13], v[104:105]
	v_pk_fma_f32 v[106:107], v[208:209], v[12:13], v[106:107]
	v_pk_fma_f32 v[104:105], v[6:7], v[14:15], v[104:105]
	v_pk_fma_f32 v[106:107], v[210:211], v[14:15], v[106:107]
	v_add_f32_e32 v108, v104, v105
	v_add_f32_e32 v110, v106, v107
	v_pk_mul_f32 v[112:113], v[32:33], v[186:187] op_sel_hi:[1,0]
	v_add_f32_dpp v108, v108, v108 quad_perm:[1,0,3,2] row_mask:0xf bank_mask:0xf bound_ctrl:1
	v_add_f32_dpp v110, v110, v110 quad_perm:[1,0,3,2] row_mask:0xf bank_mask:0xf bound_ctrl:1
	v_pk_mul_f32 v[120:121], v[32:33], v[190:191] op_sel_hi:[1,0]
	v_add_f32_dpp v108, v108, v108 quad_perm:[2,3,0,1] row_mask:0xf bank_mask:0xf bound_ctrl:1
	v_add_f32_dpp v110, v110, v110 quad_perm:[2,3,0,1] row_mask:0xf bank_mask:0xf bound_ctrl:1
	v_pk_mul_f32 v[114:115], v[34:35], v[186:187] op_sel_hi:[1,0]
	v_add_f32_dpp v108, v108, v108 row_half_mirror row_mask:0xf bank_mask:0xf bound_ctrl:1
	v_add_f32_dpp v110, v110, v110 row_half_mirror row_mask:0xf bank_mask:0xf bound_ctrl:1
	v_pk_mul_f32 v[122:123], v[34:35], v[190:191] op_sel_hi:[1,0]
	v_pk_mul_f32 v[116:117], v[36:37], v[186:187] op_sel_hi:[1,0]
	v_pk_mul_f32 v[124:125], v[36:37], v[190:191] op_sel_hi:[1,0]
	v_pk_mul_f32 v[118:119], v[38:39], v[186:187] op_sel_hi:[1,0]
	v_pk_mul_f32 v[126:127], v[38:39], v[190:191] op_sel_hi:[1,0]
	v_pk_fma_f32 v[112:113], v[108:109], v[24:25], v[112:113] op_sel_hi:[0,1,1] neg_lo:[1,0,0] neg_hi:[1,0,0]
	v_pk_fma_f32 v[120:121], v[110:111], v[24:25], v[120:121] op_sel_hi:[0,1,1] neg_lo:[1,0,0] neg_hi:[1,0,0]
	v_pk_fma_f32 v[114:115], v[108:109], v[26:27], v[114:115] op_sel_hi:[0,1,1] neg_lo:[1,0,0] neg_hi:[1,0,0]
	v_pk_fma_f32 v[122:123], v[110:111], v[26:27], v[122:123] op_sel_hi:[0,1,1] neg_lo:[1,0,0] neg_hi:[1,0,0]
	v_pk_fma_f32 v[116:117], v[108:109], v[28:29], v[116:117] op_sel_hi:[0,1,1] neg_lo:[1,0,0] neg_hi:[1,0,0]
	v_pk_fma_f32 v[124:125], v[110:111], v[28:29], v[124:125] op_sel_hi:[0,1,1] neg_lo:[1,0,0] neg_hi:[1,0,0]
	v_pk_fma_f32 v[118:119], v[108:109], v[30:31], v[118:119] op_sel_hi:[0,1,1] neg_lo:[1,0,0] neg_hi:[1,0,0]
	v_pk_fma_f32 v[126:127], v[110:111], v[30:31], v[126:127] op_sel_hi:[0,1,1] neg_lo:[1,0,0] neg_hi:[1,0,0]
	v_pk_fma_f32 v[0:1], v[0:1], v[16:17], v[112:113]
	v_pk_fma_f32 v[204:205], v[204:205], v[16:17], v[120:121]
	v_pk_fma_f32 v[2:3], v[2:3], v[18:19], v[114:115]
	v_pk_fma_f32 v[206:207], v[206:207], v[18:19], v[122:123]
	v_pk_fma_f32 v[4:5], v[4:5], v[20:21], v[116:117]
	v_pk_fma_f32 v[208:209], v[208:209], v[20:21], v[124:125]
	v_pk_fma_f32 v[6:7], v[6:7], v[22:23], v[118:119]
	v_pk_fma_f32 v[210:211], v[210:211], v[22:23], v[126:127]
	v_pk_fma_f32 v[128:129], v[0:1], v[48:49], 0 op_sel_hi:[1,1,0]
	v_pk_fma_f32 v[130:131], v[204:205], v[48:49], 0 op_sel_hi:[1,1,0]
	v_pk_fma_f32 v[128:129], v[2:3], v[50:51], v[128:129]
	v_pk_fma_f32 v[130:131], v[206:207], v[50:51], v[130:131]
	v_pk_fma_f32 v[128:129], v[4:5], v[52:53], v[128:129]
	v_pk_fma_f32 v[130:131], v[208:209], v[52:53], v[130:131]
	v_pk_fma_f32 v[128:129], v[6:7], v[54:55], v[128:129]
	v_pk_fma_f32 v[130:131], v[210:211], v[54:55], v[130:131]
	v_add_f32_e32 v102, v128, v129
	v_add_f32_e32 v103, v130, v131
	s_waitcnt lgkmcnt(0)
; template <int KT>
; __device__ __forceinline__ void scan_block(const Ctx& C, const PV& P, int layer, int sq, int h, int d, int row0, unsigned char* smem) {
;     ...
;             for (int i = 0; i < CH; ++i) {
;                 f32x2 kk2[KT / 2], w2[KT / 2], b2[KT / 2], kd2[KT / 2], r2[KT / 2];
; #pragma unroll
;                 for (int u = 0; u < KT / 4; ++u) {
;                     kk2[2 * u] = (f32x2){nx[0][u][0], nx[0][u][1]}; kk2[2 * u + 1] = (f32x2){nx[0][u][2], nx[0][u][3]};
;                     w2[2 * u] = (f32x2){nx[1][u][0], nx[1][u][1]}; w2[2 * u + 1] = (f32x2){nx[1][u][2], nx[1][u][3]};
;                     b2[2 * u] = (f32x2){nx[2][u][0], nx[2][u][1]}; b2[2 * u + 1] = (f32x2){nx[2][u][2], nx[2][u][3]};
;                     kd2[2 * u] = (f32x2){nx[3][u][0], nx[3][u][1]}; kd2[2 * u + 1] = (f32x2){nx[3][u][2], nx[3][u][3]};
;                     r2[2 * u] = (f32x2){nx[4][u][0], nx[4][u][1]}; r2[2 * u + 1] = (f32x2){nx[4][u][2], nx[4][u][3]};
;                 }
;                 const float vv = nvv;
;                 if (i + 1 < CH) {
; #pragma unroll
;                     for (int u = 0; u < KT / 4; ++u)
; #pragma unroll
;                         for (int a5 = 0; a5 < 5; ++a5) nx[a5][u] = vp0[(i + 1) * 16 + a5 * CH * 16 + u];
;                     nvv = vbuf[(i + 1) * 64 + row];
;                 }
;                 f32x2 acc2 = s[0] * kk2[0];
; #pragma unroll
;                 for (int j = 1; j < KT / 2; ++j) acc2 = __builtin_elementwise_fma(s[j], kk2[j], acc2);
;                 float sa = acc2[0] + acc2[1];
;                 sa += dppf<0xB1>(sa); sa += dppf<0x4E>(sa); sa += dppf<0x141>(sa);
;                 if (TPR == 16) sa += dppf<0x140>(sa);
;                 sa = -sa;
;                 const f32x2 sa2 = (f32x2){sa, sa}, vv2 = (f32x2){vv, vv};
;                 f32x2 y2 = (f32x2){0.f, 0.f};
; #pragma unroll
;                 for (int j = 0; j < KT / 2; ++j) {
;                     s[j] = __builtin_elementwise_fma(s[j], w2[j], __builtin_elementwise_fma(sa2, b2[j], vv2 * kd2[j]));
;                     y2 = __builtin_elementwise_fma(s[j], r2[j], y2);
;                 }
;                 float y = y2[0] + y2[1];
;                 y += dppf<0xB1>(y); y += dppf<0x4E>(y);
;                 yv[i] = y;
;             }
;             if ((q & 3) == 0) {
; #pragma unroll
	v_add_f32_dpp v102, v102, v102 quad_perm:[1,0,3,2] row_mask:0xf bank_mask:0xf bound_ctrl:1
	v_add_f32_dpp v103, v103, v103 quad_perm:[1,0,3,2] row_mask:0xf bank_mask:0xf bound_ctrl:1
	ds_read2st64_b32 v[188:189], v201 offset0:86 offset1:87
	v_add_f32_dpp v102, v102, v102 quad_perm:[2,3,0,1] row_mask:0xf bank_mask:0xf bound_ctrl:1
	v_add_f32_dpp v103, v103, v103 quad_perm:[2,3,0,1] row_mask:0xf bank_mask:0xf bound_ctrl:1
	ds_write2st64_b32 v202, v102, v103 offset0:104 offset1:105
	ds_read2st64_b32 v[192:193], v203 offset0:86 offset1:87
	ds_read_b128 v[8:11], v200 offset:1536
	ds_read_b128 v[12:15], v200 offset:1552
	ds_read_b128 v[32:35], v200 offset:13824
	ds_read_b128 v[36:39], v200 offset:13840
	ds_read_b128 v[24:27], v200 offset:9728
	ds_read_b128 v[28:31], v200 offset:9744
	ds_read_b128 v[16:19], v200 offset:5632
	ds_read_b128 v[20:23], v200 offset:5648
	ds_read_b128 v[48:51], v200 offset:17920
	ds_read_b128 v[52:55], v200 offset:17936
	v_pk_mul_f32 v[104:105], v[0:1], v[148:149]
	v_pk_mul_f32 v[106:107], v[204:205], v[148:149]
	v_pk_fma_f32 v[104:105], v[2:3], v[150:151], v[104:105]
	v_pk_fma_f32 v[106:107], v[206:207], v[150:151], v[106:107]
	v_pk_fma_f32 v[104:105], v[4:5], v[152:153], v[104:105]
	v_pk_fma_f32 v[106:107], v[208:209], v[152:153], v[106:107]
	v_pk_fma_f32 v[104:105], v[6:7], v[154:155], v[104:105]
	v_pk_fma_f32 v[106:107], v[210:211], v[154:155], v[106:107]
	v_add_f32_e32 v108, v104, v105
	v_add_f32_e32 v110, v106, v107
	v_pk_mul_f32 v[112:113], v[172:173], v[186:187] op_sel:[0,1] op_sel_hi:[1,1]
	v_add_f32_dpp v108, v108, v108 quad_perm:[1,0,3,2] row_mask:0xf bank_mask:0xf bound_ctrl:1
	v_add_f32_dpp v110, v110, v110 quad_perm:[1,0,3,2] row_mask:0xf bank_mask:0xf bound_ctrl:1
	v_pk_mul_f32 v[120:121], v[172:173], v[190:191] op_sel:[0,1] op_sel_hi:[1,1]
	v_add_f32_dpp v108, v108, v108 quad_perm:[2,3,0,1] row_mask:0xf bank_mask:0xf bound_ctrl:1
	v_add_f32_dpp v110, v110, v110 quad_perm:[2,3,0,1] row_mask:0xf bank_mask:0xf bound_ctrl:1
	v_pk_mul_f32 v[114:115], v[174:175], v[186:187] op_sel:[0,1] op_sel_hi:[1,1]
	v_add_f32_dpp v108, v108, v108 row_half_mirror row_mask:0xf bank_mask:0xf bound_ctrl:1
	v_add_f32_dpp v110, v110, v110 row_half_mirror row_mask:0xf bank_mask:0xf bound_ctrl:1
	v_pk_mul_f32 v[122:123], v[174:175], v[190:191] op_sel:[0,1] op_sel_hi:[1,1]
	v_pk_mul_f32 v[116:117], v[176:177], v[186:187] op_sel:[0,1] op_sel_hi:[1,1]
	v_pk_mul_f32 v[124:125], v[176:177], v[190:191] op_sel:[0,1] op_sel_hi:[1,1]
	v_pk_mul_f32 v[118:119], v[178:179], v[186:187] op_sel:[0,1] op_sel_hi:[1,1]
	v_pk_mul_f32 v[126:127], v[178:179], v[190:191] op_sel:[0,1] op_sel_hi:[1,1]
	v_pk_fma_f32 v[112:113], v[108:109], v[164:165], v[112:113] op_sel_hi:[0,1,1] neg_lo:[1,0,0] neg_hi:[1,0,0]
	v_pk_fma_f32 v[120:121], v[110:111], v[164:165], v[120:121] op_sel_hi:[0,1,1] neg_lo:[1,0,0] neg_hi:[1,0,0]
	v_pk_fma_f32 v[114:115], v[108:109], v[166:167], v[114:115] op_sel_hi:[0,1,1] neg_lo:[1,0,0] neg_hi:[1,0,0]
	v_pk_fma_f32 v[122:123], v[110:111], v[166:167], v[122:123] op_sel_hi:[0,1,1] neg_lo:[1,0,0] neg_hi:[1,0,0]
	v_pk_fma_f32 v[116:117], v[108:109], v[168:169], v[116:117] op_sel_hi:[0,1,1] neg_lo:[1,0,0] neg_hi:[1,0,0]
	v_pk_fma_f32 v[124:125], v[110:111], v[168:169], v[124:125] op_sel_hi:[0,1,1] neg_lo:[1,0,0] neg_hi:[1,0,0]
	v_pk_fma_f32 v[118:119], v[108:109], v[170:171], v[118:119] op_sel_hi:[0,1,1] neg_lo:[1,0,0] neg_hi:[1,0,0]
	v_pk_fma_f32 v[126:127], v[110:111], v[170:171], v[126:127] op_sel_hi:[0,1,1] neg_lo:[1,0,0] neg_hi:[1,0,0]
	v_pk_fma_f32 v[0:1], v[0:1], v[156:157], v[112:113]
	v_pk_fma_f32 v[204:205], v[204:205], v[156:157], v[120:121]
	v_pk_fma_f32 v[2:3], v[2:3], v[158:159], v[114:115]
	v_pk_fma_f32 v[206:207], v[206:207], v[158:159], v[122:123]
	v_pk_fma_f32 v[4:5], v[4:5], v[160:161], v[116:117]
	v_pk_fma_f32 v[208:209], v[208:209], v[160:161], v[124:125]
	v_pk_fma_f32 v[6:7], v[6:7], v[162:163], v[118:119]
	v_pk_fma_f32 v[210:211], v[210:211], v[162:163], v[126:127]
	v_pk_fma_f32 v[128:129], v[0:1], v[56:57], 0 op_sel_hi:[1,1,0]
	v_pk_fma_f32 v[130:131], v[204:205], v[56:57], 0 op_sel_hi:[1,1,0]
	v_pk_fma_f32 v[128:129], v[2:3], v[58:59], v[128:129]
	v_pk_fma_f32 v[130:131], v[206:207], v[58:59], v[130:131]
	v_pk_fma_f32 v[128:129], v[4:5], v[140:141], v[128:129]
	v_pk_fma_f32 v[130:131], v[208:209], v[140:141], v[130:131]
	v_pk_fma_f32 v[128:129], v[6:7], v[142:143], v[128:129]
	v_pk_fma_f32 v[130:131], v[210:211], v[142:143], v[130:131]
	v_add_f32_e32 v102, v128, v129
	v_add_f32_e32 v103, v130, v131
	s_waitcnt lgkmcnt(0)
; template <int KT>
; __device__ __forceinline__ void scan_block(const Ctx& C, const PV& P, int layer, int sq, int h, int d, int row0, unsigned char* smem) {
;     ...
;             for (int i = 0; i < CH; ++i) {
;                 f32x2 kk2[KT / 2], w2[KT / 2], b2[KT / 2], kd2[KT / 2], r2[KT / 2];
; #pragma unroll
;                 for (int u = 0; u < KT / 4; ++u) {
;                     kk2[2 * u] = (f32x2){nx[0][u][0], nx[0][u][1]}; kk2[2 * u + 1] = (f32x2){nx[0][u][2], nx[0][u][3]};
;                     w2[2 * u] = (f32x2){nx[1][u][0], nx[1][u][1]}; w2[2 * u + 1] = (f32x2){nx[1][u][2], nx[1][u][3]};
;                     b2[2 * u] = (f32x2){nx[2][u][0], nx[2][u][1]}; b2[2 * u + 1] = (f32x2){nx[2][u][2], nx[2][u][3]};
;                     kd2[2 * u] = (f32x2){nx[3][u][0], nx[3][u][1]}; kd2[2 * u + 1] = (f32x2){nx[3][u][2], nx[3][u][3]};
;                     r2[2 * u] = (f32x2){nx[4][u][0], nx[4][u][1]}; r2[2 * u + 1] = (f32x2){nx[4][u][2], nx[4][u][3]};
;                 }
;                 const float vv = nvv;
;                 if (i + 1 < CH) {
; #pragma unroll
;                     for (int u = 0; u < KT / 4; ++u)
; #pragma unroll
;                         for (int a5 = 0; a5 < 5; ++a5) nx[a5][u] = vp0[(i + 1) * 16 + a5 * CH * 16 + u];
;                     nvv = vbuf[(i + 1) * 64 + row];
;                 }
;                 f32x2 acc2 = s[0] * kk2[0];
; #pragma unroll
;                 for (int j = 1; j < KT / 2; ++j) acc2 = __builtin_elementwise_fma(s[j], kk2[j], acc2);
;                 float sa = acc2[0] + acc2[1];
;                 sa += dppf<0xB1>(sa); sa += dppf<0x4E>(sa); sa += dppf<0x141>(sa);
;                 if (TPR == 16) sa += dppf<0x140>(sa);
;                 sa = -sa;
;                 const f32x2 sa2 = (f32x2){sa, sa}, vv2 = (f32x2){vv, vv};
;                 f32x2 y2 = (f32x2){0.f, 0.f};
; #pragma unroll
;                 for (int j = 0; j < KT / 2; ++j) {
;                     s[j] = __builtin_elementwise_fma(s[j], w2[j], __builtin_elementwise_fma(sa2, b2[j], vv2 * kd2[j]));
;                     y2 = __builtin_elementwise_fma(s[j], r2[j], y2);
;                 }
;                 float y = y2[0] + y2[1];
;                 y += dppf<0xB1>(y); y += dppf<0x4E>(y);
;                 yv[i] = y;
;             }
;             if ((q & 3) == 0) {
; #pragma unroll
	v_add_f32_dpp v102, v102, v102 quad_perm:[1,0,3,2] row_mask:0xf bank_mask:0xf bound_ctrl:1
	v_add_f32_dpp v103, v103, v103 quad_perm:[1,0,3,2] row_mask:0xf bank_mask:0xf bound_ctrl:1
	ds_read_b128 v[148:151], v200 offset:1792
	v_add_f32_dpp v102, v102, v102 quad_perm:[2,3,0,1] row_mask:0xf bank_mask:0xf bound_ctrl:1
	v_add_f32_dpp v103, v103, v103 quad_perm:[2,3,0,1] row_mask:0xf bank_mask:0xf bound_ctrl:1
	ds_write2st64_b32 v202, v102, v103 offset0:106 offset1:107
	ds_read_b128 v[152:155], v200 offset:1808
	ds_read_b128 v[172:175], v200 offset:14080
	ds_read_b128 v[176:179], v200 offset:14096
	ds_read_b128 v[164:167], v200 offset:9984
	ds_read_b128 v[168:171], v200 offset:10000
	ds_read_b128 v[156:159], v200 offset:5888
	ds_read_b128 v[160:163], v200 offset:5904
	ds_read_b128 v[56:59], v200 offset:18176
	ds_read_b128 v[140:143], v200 offset:18192
	v_pk_mul_f32 v[104:105], v[0:1], v[8:9]
	v_pk_mul_f32 v[106:107], v[204:205], v[8:9]
	v_pk_fma_f32 v[104:105], v[2:3], v[10:11], v[104:105]
	v_pk_fma_f32 v[106:107], v[206:207], v[10:11], v[106:107]
	v_pk_fma_f32 v[104:105], v[4:5], v[12:13], v[104:105]
	v_pk_fma_f32 v[106:107], v[208:209], v[12:13], v[106:107]
	v_pk_fma_f32 v[104:105], v[6:7], v[14:15], v[104:105]
	v_pk_fma_f32 v[106:107], v[210:211], v[14:15], v[106:107]
	v_add_f32_e32 v108, v104, v105
	v_add_f32_e32 v110, v106, v107
	v_pk_mul_f32 v[112:113], v[32:33], v[188:189] op_sel_hi:[1,0]
	v_add_f32_dpp v108, v108, v108 quad_perm:[1,0,3,2] row_mask:0xf bank_mask:0xf bound_ctrl:1
	v_add_f32_dpp v110, v110, v110 quad_perm:[1,0,3,2] row_mask:0xf bank_mask:0xf bound_ctrl:1
	v_pk_mul_f32 v[120:121], v[32:33], v[192:193] op_sel_hi:[1,0]
	v_add_f32_dpp v108, v108, v108 quad_perm:[2,3,0,1] row_mask:0xf bank_mask:0xf bound_ctrl:1
	v_add_f32_dpp v110, v110, v110 quad_perm:[2,3,0,1] row_mask:0xf bank_mask:0xf bound_ctrl:1
	v_pk_mul_f32 v[114:115], v[34:35], v[188:189] op_sel_hi:[1,0]
	v_add_f32_dpp v108, v108, v108 row_half_mirror row_mask:0xf bank_mask:0xf bound_ctrl:1
	v_add_f32_dpp v110, v110, v110 row_half_mirror row_mask:0xf bank_mask:0xf bound_ctrl:1
	v_pk_mul_f32 v[122:123], v[34:35], v[192:193] op_sel_hi:[1,0]
	v_pk_mul_f32 v[116:117], v[36:37], v[188:189] op_sel_hi:[1,0]
	v_pk_mul_f32 v[124:125], v[36:37], v[192:193] op_sel_hi:[1,0]
	v_pk_mul_f32 v[118:119], v[38:39], v[188:189] op_sel_hi:[1,0]
	v_pk_mul_f32 v[126:127], v[38:39], v[192:193] op_sel_hi:[1,0]
	v_pk_fma_f32 v[112:113], v[108:109], v[24:25], v[112:113] op_sel_hi:[0,1,1] neg_lo:[1,0,0] neg_hi:[1,0,0]
	v_pk_fma_f32 v[120:121], v[110:111], v[24:25], v[120:121] op_sel_hi:[0,1,1] neg_lo:[1,0,0] neg_hi:[1,0,0]
	v_pk_fma_f32 v[114:115], v[108:109], v[26:27], v[114:115] op_sel_hi:[0,1,1] neg_lo:[1,0,0] neg_hi:[1,0,0]
	v_pk_fma_f32 v[122:123], v[110:111], v[26:27], v[122:123] op_sel_hi:[0,1,1] neg_lo:[1,0,0] neg_hi:[1,0,0]
	v_pk_fma_f32 v[116:117], v[108:109], v[28:29], v[116:117] op_sel_hi:[0,1,1] neg_lo:[1,0,0] neg_hi:[1,0,0]
	v_pk_fma_f32 v[124:125], v[110:111], v[28:29], v[124:125] op_sel_hi:[0,1,1] neg_lo:[1,0,0] neg_hi:[1,0,0]
	v_pk_fma_f32 v[118:119], v[108:109], v[30:31], v[118:119] op_sel_hi:[0,1,1] neg_lo:[1,0,0] neg_hi:[1,0,0]
	v_pk_fma_f32 v[126:127], v[110:111], v[30:31], v[126:127] op_sel_hi:[0,1,1] neg_lo:[1,0,0] neg_hi:[1,0,0]
	v_pk_fma_f32 v[0:1], v[0:1], v[16:17], v[112:113]
	v_pk_fma_f32 v[204:205], v[204:205], v[16:17], v[120:121]
	v_pk_fma_f32 v[2:3], v[2:3], v[18:19], v[114:115]
	v_pk_fma_f32 v[206:207], v[206:207], v[18:19], v[122:123]
	v_pk_fma_f32 v[4:5], v[4:5], v[20:21], v[116:117]
	v_pk_fma_f32 v[208:209], v[208:209], v[20:21], v[124:125]
	v_pk_fma_f32 v[6:7], v[6:7], v[22:23], v[118:119]
	v_pk_fma_f32 v[210:211], v[210:211], v[22:23], v[126:127]
	v_pk_fma_f32 v[128:129], v[0:1], v[48:49], 0 op_sel_hi:[1,1,0]
	v_pk_fma_f32 v[130:131], v[204:205], v[48:49], 0 op_sel_hi:[1,1,0]
	v_pk_fma_f32 v[128:129], v[2:3], v[50:51], v[128:129]
	v_pk_fma_f32 v[130:131], v[206:207], v[50:51], v[130:131]
	v_pk_fma_f32 v[128:129], v[4:5], v[52:53], v[128:129]
	v_pk_fma_f32 v[130:131], v[208:209], v[52:53], v[130:131]
	v_pk_fma_f32 v[128:129], v[6:7], v[54:55], v[128:129]
	v_pk_fma_f32 v[130:131], v[210:211], v[54:55], v[130:131]
	v_add_f32_e32 v102, v128, v129
	v_add_f32_e32 v103, v130, v131
	s_waitcnt lgkmcnt(0)
; template <int KT>
; __device__ __forceinline__ void scan_block(const Ctx& C, const PV& P, int layer, int sq, int h, int d, int row0, unsigned char* smem) {
;     ...
;             for (int i = 0; i < CH; ++i) {
;                 f32x2 kk2[KT / 2], w2[KT / 2], b2[KT / 2], kd2[KT / 2], r2[KT / 2];
; #pragma unroll
;                 for (int u = 0; u < KT / 4; ++u) {
;                     kk2[2 * u] = (f32x2){nx[0][u][0], nx[0][u][1]}; kk2[2 * u + 1] = (f32x2){nx[0][u][2], nx[0][u][3]};
;                     w2[2 * u] = (f32x2){nx[1][u][0], nx[1][u][1]}; w2[2 * u + 1] = (f32x2){nx[1][u][2], nx[1][u][3]};
;                     b2[2 * u] = (f32x2){nx[2][u][0], nx[2][u][1]}; b2[2 * u + 1] = (f32x2){nx[2][u][2], nx[2][u][3]};
;                     kd2[2 * u] = (f32x2){nx[3][u][0], nx[3][u][1]}; kd2[2 * u + 1] = (f32x2){nx[3][u][2], nx[3][u][3]};
;                     r2[2 * u] = (f32x2){nx[4][u][0], nx[4][u][1]}; r2[2 * u + 1] = (f32x2){nx[4][u][2], nx[4][u][3]};
;                 }
;                 const float vv = nvv;
;                 if (i + 1 < CH) {
; #pragma unroll
;                     for (int u = 0; u < KT / 4; ++u)
; #pragma unroll
;                         for (int a5 = 0; a5 < 5; ++a5) nx[a5][u] = vp0[(i + 1) * 16 + a5 * CH * 16 + u];
;                     nvv = vbuf[(i + 1) * 64 + row];
;                 }
;                 f32x2 acc2 = s[0] * kk2[0];
; #pragma unroll
;                 for (int j = 1; j < KT / 2; ++j) acc2 = __builtin_elementwise_fma(s[j], kk2[j], acc2);
;                 float sa = acc2[0] + acc2[1];
;                 sa += dppf<0xB1>(sa); sa += dppf<0x4E>(sa); sa += dppf<0x141>(sa);
;                 if (TPR == 16) sa += dppf<0x140>(sa);
;                 sa = -sa;
;                 const f32x2 sa2 = (f32x2){sa, sa}, vv2 = (f32x2){vv, vv};
;                 f32x2 y2 = (f32x2){0.f, 0.f};
; #pragma unroll
;                 for (int j = 0; j < KT / 2; ++j) {
;                     s[j] = __builtin_elementwise_fma(s[j], w2[j], __builtin_elementwise_fma(sa2, b2[j], vv2 * kd2[j]));
;                     y2 = __builtin_elementwise_fma(s[j], r2[j], y2);
;                 }
;                 float y = y2[0] + y2[1];
;                 y += dppf<0xB1>(y); y += dppf<0x4E>(y);
;                 yv[i] = y;
;             }
;             if ((q & 3) == 0) {
; #pragma unroll
	v_add_f32_dpp v102, v102, v102 quad_perm:[1,0,3,2] row_mask:0xf bank_mask:0xf bound_ctrl:1
	v_add_f32_dpp v103, v103, v103 quad_perm:[1,0,3,2] row_mask:0xf bank_mask:0xf bound_ctrl:1
	ds_read2st64_b32 v[186:187], v201 offset0:88 offset1:89
	v_add_f32_dpp v102, v102, v102 quad_perm:[2,3,0,1] row_mask:0xf bank_mask:0xf bound_ctrl:1
	v_add_f32_dpp v103, v103, v103 quad_perm:[2,3,0,1] row_mask:0xf bank_mask:0xf bound_ctrl:1
	ds_write2st64_b32 v202, v102, v103 offset0:108 offset1:109
	ds_read2st64_b32 v[190:191], v203 offset0:88 offset1:89
	ds_read_b128 v[8:11], v200 offset:2048
	ds_read_b128 v[12:15], v200 offset:2064
	ds_read_b128 v[32:35], v200 offset:14336
	ds_read_b128 v[36:39], v200 offset:14352
	ds_read_b128 v[24:27], v200 offset:10240
	ds_read_b128 v[28:31], v200 offset:10256
	ds_read_b128 v[16:19], v200 offset:6144
	ds_read_b128 v[20:23], v200 offset:6160
	ds_read_b128 v[48:51], v200 offset:18432
	ds_read_b128 v[52:55], v200 offset:18448
	v_pk_mul_f32 v[104:105], v[0:1], v[148:149]
	v_pk_mul_f32 v[106:107], v[204:205], v[148:149]
	v_pk_fma_f32 v[104:105], v[2:3], v[150:151], v[104:105]
	v_pk_fma_f32 v[106:107], v[206:207], v[150:151], v[106:107]
	v_pk_fma_f32 v[104:105], v[4:5], v[152:153], v[104:105]
	v_pk_fma_f32 v[106:107], v[208:209], v[152:153], v[106:107]
	v_pk_fma_f32 v[104:105], v[6:7], v[154:155], v[104:105]
	v_pk_fma_f32 v[106:107], v[210:211], v[154:155], v[106:107]
	v_add_f32_e32 v108, v104, v105
	v_add_f32_e32 v110, v106, v107
	v_pk_mul_f32 v[112:113], v[172:173], v[188:189] op_sel:[0,1] op_sel_hi:[1,1]
	v_add_f32_dpp v108, v108, v108 quad_perm:[1,0,3,2] row_mask:0xf bank_mask:0xf bound_ctrl:1
	v_add_f32_dpp v110, v110, v110 quad_perm:[1,0,3,2] row_mask:0xf bank_mask:0xf bound_ctrl:1
	v_pk_mul_f32 v[120:121], v[172:173], v[192:193] op_sel:[0,1] op_sel_hi:[1,1]
	v_add_f32_dpp v108, v108, v108 quad_perm:[2,3,0,1] row_mask:0xf bank_mask:0xf bound_ctrl:1
	v_add_f32_dpp v110, v110, v110 quad_perm:[2,3,0,1] row_mask:0xf bank_mask:0xf bound_ctrl:1
	v_pk_mul_f32 v[114:115], v[174:175], v[188:189] op_sel:[0,1] op_sel_hi:[1,1]
	v_add_f32_dpp v108, v108, v108 row_half_mirror row_mask:0xf bank_mask:0xf bound_ctrl:1
	v_add_f32_dpp v110, v110, v110 row_half_mirror row_mask:0xf bank_mask:0xf bound_ctrl:1
	v_pk_mul_f32 v[122:123], v[174:175], v[192:193] op_sel:[0,1] op_sel_hi:[1,1]
	v_pk_mul_f32 v[116:117], v[176:177], v[188:189] op_sel:[0,1] op_sel_hi:[1,1]
	v_pk_mul_f32 v[124:125], v[176:177], v[192:193] op_sel:[0,1] op_sel_hi:[1,1]
	v_pk_mul_f32 v[118:119], v[178:179], v[188:189] op_sel:[0,1] op_sel_hi:[1,1]
	v_pk_mul_f32 v[126:127], v[178:179], v[192:193] op_sel:[0,1] op_sel_hi:[1,1]
	v_pk_fma_f32 v[112:113], v[108:109], v[164:165], v[112:113] op_sel_hi:[0,1,1] neg_lo:[1,0,0] neg_hi:[1,0,0]
	v_pk_fma_f32 v[120:121], v[110:111], v[164:165], v[120:121] op_sel_hi:[0,1,1] neg_lo:[1,0,0] neg_hi:[1,0,0]
	v_pk_fma_f32 v[114:115], v[108:109], v[166:167], v[114:115] op_sel_hi:[0,1,1] neg_lo:[1,0,0] neg_hi:[1,0,0]
	v_pk_fma_f32 v[122:123], v[110:111], v[166:167], v[122:123] op_sel_hi:[0,1,1] neg_lo:[1,0,0] neg_hi:[1,0,0]
	v_pk_fma_f32 v[116:117], v[108:109], v[168:169], v[116:117] op_sel_hi:[0,1,1] neg_lo:[1,0,0] neg_hi:[1,0,0]
	v_pk_fma_f32 v[124:125], v[110:111], v[168:169], v[124:125] op_sel_hi:[0,1,1] neg_lo:[1,0,0] neg_hi:[1,0,0]
	v_pk_fma_f32 v[118:119], v[108:109], v[170:171], v[118:119] op_sel_hi:[0,1,1] neg_lo:[1,0,0] neg_hi:[1,0,0]
	v_pk_fma_f32 v[126:127], v[110:111], v[170:171], v[126:127] op_sel_hi:[0,1,1] neg_lo:[1,0,0] neg_hi:[1,0,0]
	v_pk_fma_f32 v[0:1], v[0:1], v[156:157], v[112:113]
	v_pk_fma_f32 v[204:205], v[204:205], v[156:157], v[120:121]
	v_pk_fma_f32 v[2:3], v[2:3], v[158:159], v[114:115]
	v_pk_fma_f32 v[206:207], v[206:207], v[158:159], v[122:123]
	v_pk_fma_f32 v[4:5], v[4:5], v[160:161], v[116:117]
	v_pk_fma_f32 v[208:209], v[208:209], v[160:161], v[124:125]
	v_pk_fma_f32 v[6:7], v[6:7], v[162:163], v[118:119]
	v_pk_fma_f32 v[210:211], v[210:211], v[162:163], v[126:127]
	v_pk_fma_f32 v[128:129], v[0:1], v[56:57], 0 op_sel_hi:[1,1,0]
	v_pk_fma_f32 v[130:131], v[204:205], v[56:57], 0 op_sel_hi:[1,1,0]
	v_pk_fma_f32 v[128:129], v[2:3], v[58:59], v[128:129]
	v_pk_fma_f32 v[130:131], v[206:207], v[58:59], v[130:131]
	v_pk_fma_f32 v[128:129], v[4:5], v[140:141], v[128:129]
	v_pk_fma_f32 v[130:131], v[208:209], v[140:141], v[130:131]
	v_pk_fma_f32 v[128:129], v[6:7], v[142:143], v[128:129]
	v_pk_fma_f32 v[130:131], v[210:211], v[142:143], v[130:131]
	v_add_f32_e32 v102, v128, v129
	v_add_f32_e32 v103, v130, v131
	s_waitcnt lgkmcnt(0)
; template <int KT>
; __device__ __forceinline__ void scan_block(const Ctx& C, const PV& P, int layer, int sq, int h, int d, int row0, unsigned char* smem) {
;     ...
;             for (int i = 0; i < CH; ++i) {
;                 f32x2 kk2[KT / 2], w2[KT / 2], b2[KT / 2], kd2[KT / 2], r2[KT / 2];
; #pragma unroll
;                 for (int u = 0; u < KT / 4; ++u) {
;                     kk2[2 * u] = (f32x2){nx[0][u][0], nx[0][u][1]}; kk2[2 * u + 1] = (f32x2){nx[0][u][2], nx[0][u][3]};
;                     w2[2 * u] = (f32x2){nx[1][u][0], nx[1][u][1]}; w2[2 * u + 1] = (f32x2){nx[1][u][2], nx[1][u][3]};
;                     b2[2 * u] = (f32x2){nx[2][u][0], nx[2][u][1]}; b2[2 * u + 1] = (f32x2){nx[2][u][2], nx[2][u][3]};
;                     kd2[2 * u] = (f32x2){nx[3][u][0], nx[3][u][1]}; kd2[2 * u + 1] = (f32x2){nx[3][u][2], nx[3][u][3]};
;                     r2[2 * u] = (f32x2){nx[4][u][0], nx[4][u][1]}; r2[2 * u + 1] = (f32x2){nx[4][u][2], nx[4][u][3]};
;                 }
;                 const float vv = nvv;
;                 if (i + 1 < CH) {
; #pragma unroll
;                     for (int u = 0; u < KT / 4; ++u)
; #pragma unroll
;                         for (int a5 = 0; a5 < 5; ++a5) nx[a5][u] = vp0[(i + 1) * 16 + a5 * CH * 16 + u];
;                     nvv = vbuf[(i + 1) * 64 + row];
;                 }
;                 f32x2 acc2 = s[0] * kk2[0];
; #pragma unroll
;                 for (int j = 1; j < KT / 2; ++j) acc2 = __builtin_elementwise_fma(s[j], kk2[j], acc2);
;                 float sa = acc2[0] + acc2[1];
;                 sa += dppf<0xB1>(sa); sa += dppf<0x4E>(sa); sa += dppf<0x141>(sa);
;                 if (TPR == 16) sa += dppf<0x140>(sa);
;                 sa = -sa;
;                 const f32x2 sa2 = (f32x2){sa, sa}, vv2 = (f32x2){vv, vv};
;                 f32x2 y2 = (f32x2){0.f, 0.f};
; #pragma unroll
;                 for (int j = 0; j < KT / 2; ++j) {
;                     s[j] = __builtin_elementwise_fma(s[j], w2[j], __builtin_elementwise_fma(sa2, b2[j], vv2 * kd2[j]));
;                     y2 = __builtin_elementwise_fma(s[j], r2[j], y2);
;                 }
;                 float y = y2[0] + y2[1];
;                 y += dppf<0xB1>(y); y += dppf<0x4E>(y);
;                 yv[i] = y;
;             }
;             if ((q & 3) == 0) {
; #pragma unroll
	v_add_f32_dpp v102, v102, v102 quad_perm:[1,0,3,2] row_mask:0xf bank_mask:0xf bound_ctrl:1
	v_add_f32_dpp v103, v103, v103 quad_perm:[1,0,3,2] row_mask:0xf bank_mask:0xf bound_ctrl:1
	ds_read_b128 v[148:151], v200 offset:2304
	v_add_f32_dpp v102, v102, v102 quad_perm:[2,3,0,1] row_mask:0xf bank_mask:0xf bound_ctrl:1
	v_add_f32_dpp v103, v103, v103 quad_perm:[2,3,0,1] row_mask:0xf bank_mask:0xf bound_ctrl:1
	ds_write2st64_b32 v202, v102, v103 offset0:110 offset1:111
	ds_read_b128 v[152:155], v200 offset:2320
	ds_read_b128 v[172:175], v200 offset:14592
	ds_read_b128 v[176:179], v200 offset:14608
	ds_read_b128 v[164:167], v200 offset:10496
	ds_read_b128 v[168:171], v200 offset:10512
	ds_read_b128 v[156:159], v200 offset:6400
	ds_read_b128 v[160:163], v200 offset:6416
	ds_read_b128 v[56:59], v200 offset:18688
	ds_read_b128 v[140:143], v200 offset:18704
	v_pk_mul_f32 v[104:105], v[0:1], v[8:9]
	v_pk_mul_f32 v[106:107], v[204:205], v[8:9]
	v_pk_fma_f32 v[104:105], v[2:3], v[10:11], v[104:105]
	v_pk_fma_f32 v[106:107], v[206:207], v[10:11], v[106:107]
	v_pk_fma_f32 v[104:105], v[4:5], v[12:13], v[104:105]
	v_pk_fma_f32 v[106:107], v[208:209], v[12:13], v[106:107]
	v_pk_fma_f32 v[104:105], v[6:7], v[14:15], v[104:105]
	v_pk_fma_f32 v[106:107], v[210:211], v[14:15], v[106:107]
	v_add_f32_e32 v108, v104, v105
	v_add_f32_e32 v110, v106, v107
	v_pk_mul_f32 v[112:113], v[32:33], v[186:187] op_sel_hi:[1,0]
	v_add_f32_dpp v108, v108, v108 quad_perm:[1,0,3,2] row_mask:0xf bank_mask:0xf bound_ctrl:1
	v_add_f32_dpp v110, v110, v110 quad_perm:[1,0,3,2] row_mask:0xf bank_mask:0xf bound_ctrl:1
	v_pk_mul_f32 v[120:121], v[32:33], v[190:191] op_sel_hi:[1,0]
	v_add_f32_dpp v108, v108, v108 quad_perm:[2,3,0,1] row_mask:0xf bank_mask:0xf bound_ctrl:1
	v_add_f32_dpp v110, v110, v110 quad_perm:[2,3,0,1] row_mask:0xf bank_mask:0xf bound_ctrl:1
	v_pk_mul_f32 v[114:115], v[34:35], v[186:187] op_sel_hi:[1,0]
	v_add_f32_dpp v108, v108, v108 row_half_mirror row_mask:0xf bank_mask:0xf bound_ctrl:1
	v_add_f32_dpp v110, v110, v110 row_half_mirror row_mask:0xf bank_mask:0xf bound_ctrl:1
	v_pk_mul_f32 v[122:123], v[34:35], v[190:191] op_sel_hi:[1,0]
	v_pk_mul_f32 v[116:117], v[36:37], v[186:187] op_sel_hi:[1,0]
	v_pk_mul_f32 v[124:125], v[36:37], v[190:191] op_sel_hi:[1,0]
	v_pk_mul_f32 v[118:119], v[38:39], v[186:187] op_sel_hi:[1,0]
	v_pk_mul_f32 v[126:127], v[38:39], v[190:191] op_sel_hi:[1,0]
	v_pk_fma_f32 v[112:113], v[108:109], v[24:25], v[112:113] op_sel_hi:[0,1,1] neg_lo:[1,0,0] neg_hi:[1,0,0]
	v_pk_fma_f32 v[120:121], v[110:111], v[24:25], v[120:121] op_sel_hi:[0,1,1] neg_lo:[1,0,0] neg_hi:[1,0,0]
	v_pk_fma_f32 v[114:115], v[108:109], v[26:27], v[114:115] op_sel_hi:[0,1,1] neg_lo:[1,0,0] neg_hi:[1,0,0]
	v_pk_fma_f32 v[122:123], v[110:111], v[26:27], v[122:123] op_sel_hi:[0,1,1] neg_lo:[1,0,0] neg_hi:[1,0,0]
	v_pk_fma_f32 v[116:117], v[108:109], v[28:29], v[116:117] op_sel_hi:[0,1,1] neg_lo:[1,0,0] neg_hi:[1,0,0]
	v_pk_fma_f32 v[124:125], v[110:111], v[28:29], v[124:125] op_sel_hi:[0,1,1] neg_lo:[1,0,0] neg_hi:[1,0,0]
	v_pk_fma_f32 v[118:119], v[108:109], v[30:31], v[118:119] op_sel_hi:[0,1,1] neg_lo:[1,0,0] neg_hi:[1,0,0]
	v_pk_fma_f32 v[126:127], v[110:111], v[30:31], v[126:127] op_sel_hi:[0,1,1] neg_lo:[1,0,0] neg_hi:[1,0,0]
	v_pk_fma_f32 v[0:1], v[0:1], v[16:17], v[112:113]
	v_pk_fma_f32 v[204:205], v[204:205], v[16:17], v[120:121]
	v_pk_fma_f32 v[2:3], v[2:3], v[18:19], v[114:115]
	v_pk_fma_f32 v[206:207], v[206:207], v[18:19], v[122:123]
	v_pk_fma_f32 v[4:5], v[4:5], v[20:21], v[116:117]
	v_pk_fma_f32 v[208:209], v[208:209], v[20:21], v[124:125]
	v_pk_fma_f32 v[6:7], v[6:7], v[22:23], v[118:119]
	v_pk_fma_f32 v[210:211], v[210:211], v[22:23], v[126:127]
	v_pk_fma_f32 v[128:129], v[0:1], v[48:49], 0 op_sel_hi:[1,1,0]
	v_pk_fma_f32 v[130:131], v[204:205], v[48:49], 0 op_sel_hi:[1,1,0]
	v_pk_fma_f32 v[128:129], v[2:3], v[50:51], v[128:129]
	v_pk_fma_f32 v[130:131], v[206:207], v[50:51], v[130:131]
	v_pk_fma_f32 v[128:129], v[4:5], v[52:53], v[128:129]
	v_pk_fma_f32 v[130:131], v[208:209], v[52:53], v[130:131]
	v_pk_fma_f32 v[128:129], v[6:7], v[54:55], v[128:129]
	v_pk_fma_f32 v[130:131], v[210:211], v[54:55], v[130:131]
	v_add_f32_e32 v102, v128, v129
	v_add_f32_e32 v103, v130, v131
	s_waitcnt lgkmcnt(0)
; template <int KT>
; __device__ __forceinline__ void scan_block(const Ctx& C, const PV& P, int layer, int sq, int h, int d, int row0, unsigned char* smem) {
;     ...
;             for (int i = 0; i < CH; ++i) {
;                 f32x2 kk2[KT / 2], w2[KT / 2], b2[KT / 2], kd2[KT / 2], r2[KT / 2];
; #pragma unroll
;                 for (int u = 0; u < KT / 4; ++u) {
;                     kk2[2 * u] = (f32x2){nx[0][u][0], nx[0][u][1]}; kk2[2 * u + 1] = (f32x2){nx[0][u][2], nx[0][u][3]};
;                     w2[2 * u] = (f32x2){nx[1][u][0], nx[1][u][1]}; w2[2 * u + 1] = (f32x2){nx[1][u][2], nx[1][u][3]};
;                     b2[2 * u] = (f32x2){nx[2][u][0], nx[2][u][1]}; b2[2 * u + 1] = (f32x2){nx[2][u][2], nx[2][u][3]};
;                     kd2[2 * u] = (f32x2){nx[3][u][0], nx[3][u][1]}; kd2[2 * u + 1] = (f32x2){nx[3][u][2], nx[3][u][3]};
;                     r2[2 * u] = (f32x2){nx[4][u][0], nx[4][u][1]}; r2[2 * u + 1] = (f32x2){nx[4][u][2], nx[4][u][3]};
;                 }
;                 const float vv = nvv;
;                 if (i + 1 < CH) {
; #pragma unroll
;                     for (int u = 0; u < KT / 4; ++u)
; #pragma unroll
;                         for (int a5 = 0; a5 < 5; ++a5) nx[a5][u] = vp0[(i + 1) * 16 + a5 * CH * 16 + u];
;                     nvv = vbuf[(i + 1) * 64 + row];
;                 }
;                 f32x2 acc2 = s[0] * kk2[0];
; #pragma unroll
;                 for (int j = 1; j < KT / 2; ++j) acc2 = __builtin_elementwise_fma(s[j], kk2[j], acc2);
;                 float sa = acc2[0] + acc2[1];
;                 sa += dppf<0xB1>(sa); sa += dppf<0x4E>(sa); sa += dppf<0x141>(sa);
;                 if (TPR == 16) sa += dppf<0x140>(sa);
;                 sa = -sa;
;                 const f32x2 sa2 = (f32x2){sa, sa}, vv2 = (f32x2){vv, vv};
;                 f32x2 y2 = (f32x2){0.f, 0.f};
; #pragma unroll
;                 for (int j = 0; j < KT / 2; ++j) {
;                     s[j] = __builtin_elementwise_fma(s[j], w2[j], __builtin_elementwise_fma(sa2, b2[j], vv2 * kd2[j]));
;                     y2 = __builtin_elementwise_fma(s[j], r2[j], y2);
;                 }
;                 float y = y2[0] + y2[1];
;                 y += dppf<0xB1>(y); y += dppf<0x4E>(y);
;                 yv[i] = y;
;             }
;             if ((q & 3) == 0) {
; #pragma unroll
	v_add_f32_dpp v102, v102, v102 quad_perm:[1,0,3,2] row_mask:0xf bank_mask:0xf bound_ctrl:1
	v_add_f32_dpp v103, v103, v103 quad_perm:[1,0,3,2] row_mask:0xf bank_mask:0xf bound_ctrl:1
	ds_read2st64_b32 v[188:189], v201 offset0:90 offset1:91
	v_add_f32_dpp v102, v102, v102 quad_perm:[2,3,0,1] row_mask:0xf bank_mask:0xf bound_ctrl:1
	v_add_f32_dpp v103, v103, v103 quad_perm:[2,3,0,1] row_mask:0xf bank_mask:0xf bound_ctrl:1
	ds_write2st64_b32 v202, v102, v103 offset0:112 offset1:113
	ds_read2st64_b32 v[192:193], v203 offset0:90 offset1:91
	ds_read_b128 v[8:11], v200 offset:2560
	ds_read_b128 v[12:15], v200 offset:2576
	ds_read_b128 v[32:35], v200 offset:14848
	ds_read_b128 v[36:39], v200 offset:14864
	ds_read_b128 v[24:27], v200 offset:10752
	ds_read_b128 v[28:31], v200 offset:10768
	ds_read_b128 v[16:19], v200 offset:6656
	ds_read_b128 v[20:23], v200 offset:6672
	ds_read_b128 v[48:51], v200 offset:18944
	ds_read_b128 v[52:55], v200 offset:18960
	v_pk_mul_f32 v[104:105], v[0:1], v[148:149]
	v_pk_mul_f32 v[106:107], v[204:205], v[148:149]
	v_pk_fma_f32 v[104:105], v[2:3], v[150:151], v[104:105]
	v_pk_fma_f32 v[106:107], v[206:207], v[150:151], v[106:107]
	v_pk_fma_f32 v[104:105], v[4:5], v[152:153], v[104:105]
	v_pk_fma_f32 v[106:107], v[208:209], v[152:153], v[106:107]
	v_pk_fma_f32 v[104:105], v[6:7], v[154:155], v[104:105]
	v_pk_fma_f32 v[106:107], v[210:211], v[154:155], v[106:107]
	v_add_f32_e32 v108, v104, v105
	v_add_f32_e32 v110, v106, v107
	v_pk_mul_f32 v[112:113], v[172:173], v[186:187] op_sel:[0,1] op_sel_hi:[1,1]
	v_add_f32_dpp v108, v108, v108 quad_perm:[1,0,3,2] row_mask:0xf bank_mask:0xf bound_ctrl:1
	v_add_f32_dpp v110, v110, v110 quad_perm:[1,0,3,2] row_mask:0xf bank_mask:0xf bound_ctrl:1
	v_pk_mul_f32 v[120:121], v[172:173], v[190:191] op_sel:[0,1] op_sel_hi:[1,1]
	v_add_f32_dpp v108, v108, v108 quad_perm:[2,3,0,1] row_mask:0xf bank_mask:0xf bound_ctrl:1
	v_add_f32_dpp v110, v110, v110 quad_perm:[2,3,0,1] row_mask:0xf bank_mask:0xf bound_ctrl:1
	v_pk_mul_f32 v[114:115], v[174:175], v[186:187] op_sel:[0,1] op_sel_hi:[1,1]
	v_add_f32_dpp v108, v108, v108 row_half_mirror row_mask:0xf bank_mask:0xf bound_ctrl:1
	v_add_f32_dpp v110, v110, v110 row_half_mirror row_mask:0xf bank_mask:0xf bound_ctrl:1
	v_pk_mul_f32 v[122:123], v[174:175], v[190:191] op_sel:[0,1] op_sel_hi:[1,1]
	v_pk_mul_f32 v[116:117], v[176:177], v[186:187] op_sel:[0,1] op_sel_hi:[1,1]
	v_pk_mul_f32 v[124:125], v[176:177], v[190:191] op_sel:[0,1] op_sel_hi:[1,1]
	v_pk_mul_f32 v[118:119], v[178:179], v[186:187] op_sel:[0,1] op_sel_hi:[1,1]
	v_pk_mul_f32 v[126:127], v[178:179], v[190:191] op_sel:[0,1] op_sel_hi:[1,1]
	v_pk_fma_f32 v[112:113], v[108:109], v[164:165], v[112:113] op_sel_hi:[0,1,1] neg_lo:[1,0,0] neg_hi:[1,0,0]
	v_pk_fma_f32 v[120:121], v[110:111], v[164:165], v[120:121] op_sel_hi:[0,1,1] neg_lo:[1,0,0] neg_hi:[1,0,0]
	v_pk_fma_f32 v[114:115], v[108:109], v[166:167], v[114:115] op_sel_hi:[0,1,1] neg_lo:[1,0,0] neg_hi:[1,0,0]
	v_pk_fma_f32 v[122:123], v[110:111], v[166:167], v[122:123] op_sel_hi:[0,1,1] neg_lo:[1,0,0] neg_hi:[1,0,0]
	v_pk_fma_f32 v[116:117], v[108:109], v[168:169], v[116:117] op_sel_hi:[0,1,1] neg_lo:[1,0,0] neg_hi:[1,0,0]
	v_pk_fma_f32 v[124:125], v[110:111], v[168:169], v[124:125] op_sel_hi:[0,1,1] neg_lo:[1,0,0] neg_hi:[1,0,0]
	v_pk_fma_f32 v[118:119], v[108:109], v[170:171], v[118:119] op_sel_hi:[0,1,1] neg_lo:[1,0,0] neg_hi:[1,0,0]
	v_pk_fma_f32 v[126:127], v[110:111], v[170:171], v[126:127] op_sel_hi:[0,1,1] neg_lo:[1,0,0] neg_hi:[1,0,0]
	v_pk_fma_f32 v[0:1], v[0:1], v[156:157], v[112:113]
	v_pk_fma_f32 v[204:205], v[204:205], v[156:157], v[120:121]
	v_pk_fma_f32 v[2:3], v[2:3], v[158:159], v[114:115]
	v_pk_fma_f32 v[206:207], v[206:207], v[158:159], v[122:123]
	v_pk_fma_f32 v[4:5], v[4:5], v[160:161], v[116:117]
	v_pk_fma_f32 v[208:209], v[208:209], v[160:161], v[124:125]
	v_pk_fma_f32 v[6:7], v[6:7], v[162:163], v[118:119]
	v_pk_fma_f32 v[210:211], v[210:211], v[162:163], v[126:127]
	v_pk_fma_f32 v[128:129], v[0:1], v[56:57], 0 op_sel_hi:[1,1,0]
	v_pk_fma_f32 v[130:131], v[204:205], v[56:57], 0 op_sel_hi:[1,1,0]
	v_pk_fma_f32 v[128:129], v[2:3], v[58:59], v[128:129]
	v_pk_fma_f32 v[130:131], v[206:207], v[58:59], v[130:131]
	v_pk_fma_f32 v[128:129], v[4:5], v[140:141], v[128:129]
	v_pk_fma_f32 v[130:131], v[208:209], v[140:141], v[130:131]
	v_pk_fma_f32 v[128:129], v[6:7], v[142:143], v[128:129]
	v_pk_fma_f32 v[130:131], v[210:211], v[142:143], v[130:131]
	v_add_f32_e32 v102, v128, v129
	v_add_f32_e32 v103, v130, v131
	s_waitcnt lgkmcnt(0)
; template <int KT>
; __device__ __forceinline__ void scan_block(const Ctx& C, const PV& P, int layer, int sq, int h, int d, int row0, unsigned char* smem) {
;     ...
;             for (int i = 0; i < CH; ++i) {
;                 f32x2 kk2[KT / 2], w2[KT / 2], b2[KT / 2], kd2[KT / 2], r2[KT / 2];
; #pragma unroll
;                 for (int u = 0; u < KT / 4; ++u) {
;                     kk2[2 * u] = (f32x2){nx[0][u][0], nx[0][u][1]}; kk2[2 * u + 1] = (f32x2){nx[0][u][2], nx[0][u][3]};
;                     w2[2 * u] = (f32x2){nx[1][u][0], nx[1][u][1]}; w2[2 * u + 1] = (f32x2){nx[1][u][2], nx[1][u][3]};
;                     b2[2 * u] = (f32x2){nx[2][u][0], nx[2][u][1]}; b2[2 * u + 1] = (f32x2){nx[2][u][2], nx[2][u][3]};
;                     kd2[2 * u] = (f32x2){nx[3][u][0], nx[3][u][1]}; kd2[2 * u + 1] = (f32x2){nx[3][u][2], nx[3][u][3]};
;                     r2[2 * u] = (f32x2){nx[4][u][0], nx[4][u][1]}; r2[2 * u + 1] = (f32x2){nx[4][u][2], nx[4][u][3]};
;                 }
;                 const float vv = nvv;
;                 if (i + 1 < CH) {
; #pragma unroll
;                     for (int u = 0; u < KT / 4; ++u)
; #pragma unroll
;                         for (int a5 = 0; a5 < 5; ++a5) nx[a5][u] = vp0[(i + 1) * 16 + a5 * CH * 16 + u];
;                     nvv = vbuf[(i + 1) * 64 + row];
;                 }
;                 f32x2 acc2 = s[0] * kk2[0];
; #pragma unroll
;                 for (int j = 1; j < KT / 2; ++j) acc2 = __builtin_elementwise_fma(s[j], kk2[j], acc2);
;                 float sa = acc2[0] + acc2[1];
;                 sa += dppf<0xB1>(sa); sa += dppf<0x4E>(sa); sa += dppf<0x141>(sa);
;                 if (TPR == 16) sa += dppf<0x140>(sa);
;                 sa = -sa;
;                 const f32x2 sa2 = (f32x2){sa, sa}, vv2 = (f32x2){vv, vv};
;                 f32x2 y2 = (f32x2){0.f, 0.f};
; #pragma unroll
;                 for (int j = 0; j < KT / 2; ++j) {
;                     s[j] = __builtin_elementwise_fma(s[j], w2[j], __builtin_elementwise_fma(sa2, b2[j], vv2 * kd2[j]));
;                     y2 = __builtin_elementwise_fma(s[j], r2[j], y2);
;                 }
;                 float y = y2[0] + y2[1];
;                 y += dppf<0xB1>(y); y += dppf<0x4E>(y);
;                 yv[i] = y;
;             }
;             if ((q & 3) == 0) {
; #pragma unroll
	v_add_f32_dpp v102, v102, v102 quad_perm:[1,0,3,2] row_mask:0xf bank_mask:0xf bound_ctrl:1
	v_add_f32_dpp v103, v103, v103 quad_perm:[1,0,3,2] row_mask:0xf bank_mask:0xf bound_ctrl:1
	ds_read_b128 v[148:151], v200 offset:2816
	v_add_f32_dpp v102, v102, v102 quad_perm:[2,3,0,1] row_mask:0xf bank_mask:0xf bound_ctrl:1
	v_add_f32_dpp v103, v103, v103 quad_perm:[2,3,0,1] row_mask:0xf bank_mask:0xf bound_ctrl:1
	ds_write2st64_b32 v202, v102, v103 offset0:114 offset1:115
	ds_read_b128 v[152:155], v200 offset:2832
	ds_read_b128 v[172:175], v200 offset:15104
	ds_read_b128 v[176:179], v200 offset:15120
	ds_read_b128 v[164:167], v200 offset:11008
	ds_read_b128 v[168:171], v200 offset:11024
	ds_read_b128 v[156:159], v200 offset:6912
	ds_read_b128 v[160:163], v200 offset:6928
	ds_read_b128 v[56:59], v200 offset:19200
	ds_read_b128 v[140:143], v200 offset:19216
	v_pk_mul_f32 v[104:105], v[0:1], v[8:9]
	v_pk_mul_f32 v[106:107], v[204:205], v[8:9]
	v_pk_fma_f32 v[104:105], v[2:3], v[10:11], v[104:105]
	v_pk_fma_f32 v[106:107], v[206:207], v[10:11], v[106:107]
	v_pk_fma_f32 v[104:105], v[4:5], v[12:13], v[104:105]
	v_pk_fma_f32 v[106:107], v[208:209], v[12:13], v[106:107]
	v_pk_fma_f32 v[104:105], v[6:7], v[14:15], v[104:105]
	v_pk_fma_f32 v[106:107], v[210:211], v[14:15], v[106:107]
	v_add_f32_e32 v108, v104, v105
	v_add_f32_e32 v110, v106, v107
	v_pk_mul_f32 v[112:113], v[32:33], v[188:189] op_sel_hi:[1,0]
	v_add_f32_dpp v108, v108, v108 quad_perm:[1,0,3,2] row_mask:0xf bank_mask:0xf bound_ctrl:1
	v_add_f32_dpp v110, v110, v110 quad_perm:[1,0,3,2] row_mask:0xf bank_mask:0xf bound_ctrl:1
	v_pk_mul_f32 v[120:121], v[32:33], v[192:193] op_sel_hi:[1,0]
	v_add_f32_dpp v108, v108, v108 quad_perm:[2,3,0,1] row_mask:0xf bank_mask:0xf bound_ctrl:1
	v_add_f32_dpp v110, v110, v110 quad_perm:[2,3,0,1] row_mask:0xf bank_mask:0xf bound_ctrl:1
	v_pk_mul_f32 v[114:115], v[34:35], v[188:189] op_sel_hi:[1,0]
	v_add_f32_dpp v108, v108, v108 row_half_mirror row_mask:0xf bank_mask:0xf bound_ctrl:1
	v_add_f32_dpp v110, v110, v110 row_half_mirror row_mask:0xf bank_mask:0xf bound_ctrl:1
	v_pk_mul_f32 v[122:123], v[34:35], v[192:193] op_sel_hi:[1,0]
	v_pk_mul_f32 v[116:117], v[36:37], v[188:189] op_sel_hi:[1,0]
	v_pk_mul_f32 v[124:125], v[36:37], v[192:193] op_sel_hi:[1,0]
	v_pk_mul_f32 v[118:119], v[38:39], v[188:189] op_sel_hi:[1,0]
	v_pk_mul_f32 v[126:127], v[38:39], v[192:193] op_sel_hi:[1,0]
	v_pk_fma_f32 v[112:113], v[108:109], v[24:25], v[112:113] op_sel_hi:[0,1,1] neg_lo:[1,0,0] neg_hi:[1,0,0]
	v_pk_fma_f32 v[120:121], v[110:111], v[24:25], v[120:121] op_sel_hi:[0,1,1] neg_lo:[1,0,0] neg_hi:[1,0,0]
	v_pk_fma_f32 v[114:115], v[108:109], v[26:27], v[114:115] op_sel_hi:[0,1,1] neg_lo:[1,0,0] neg_hi:[1,0,0]
	v_pk_fma_f32 v[122:123], v[110:111], v[26:27], v[122:123] op_sel_hi:[0,1,1] neg_lo:[1,0,0] neg_hi:[1,0,0]
	v_pk_fma_f32 v[116:117], v[108:109], v[28:29], v[116:117] op_sel_hi:[0,1,1] neg_lo:[1,0,0] neg_hi:[1,0,0]
	v_pk_fma_f32 v[124:125], v[110:111], v[28:29], v[124:125] op_sel_hi:[0,1,1] neg_lo:[1,0,0] neg_hi:[1,0,0]
	v_pk_fma_f32 v[118:119], v[108:109], v[30:31], v[118:119] op_sel_hi:[0,1,1] neg_lo:[1,0,0] neg_hi:[1,0,0]
	v_pk_fma_f32 v[126:127], v[110:111], v[30:31], v[126:127] op_sel_hi:[0,1,1] neg_lo:[1,0,0] neg_hi:[1,0,0]
	v_pk_fma_f32 v[0:1], v[0:1], v[16:17], v[112:113]
	v_pk_fma_f32 v[204:205], v[204:205], v[16:17], v[120:121]
	v_pk_fma_f32 v[2:3], v[2:3], v[18:19], v[114:115]
	v_pk_fma_f32 v[206:207], v[206:207], v[18:19], v[122:123]
	v_pk_fma_f32 v[4:5], v[4:5], v[20:21], v[116:117]
	v_pk_fma_f32 v[208:209], v[208:209], v[20:21], v[124:125]
	v_pk_fma_f32 v[6:7], v[6:7], v[22:23], v[118:119]
	v_pk_fma_f32 v[210:211], v[210:211], v[22:23], v[126:127]
	v_pk_fma_f32 v[128:129], v[0:1], v[48:49], 0 op_sel_hi:[1,1,0]
	v_pk_fma_f32 v[130:131], v[204:205], v[48:49], 0 op_sel_hi:[1,1,0]
	v_pk_fma_f32 v[128:129], v[2:3], v[50:51], v[128:129]
	v_pk_fma_f32 v[130:131], v[206:207], v[50:51], v[130:131]
	v_pk_fma_f32 v[128:129], v[4:5], v[52:53], v[128:129]
	v_pk_fma_f32 v[130:131], v[208:209], v[52:53], v[130:131]
	v_pk_fma_f32 v[128:129], v[6:7], v[54:55], v[128:129]
	v_pk_fma_f32 v[130:131], v[210:211], v[54:55], v[130:131]
	v_add_f32_e32 v102, v128, v129
	v_add_f32_e32 v103, v130, v131
	s_waitcnt lgkmcnt(0)
; template <int KT>
; __device__ __forceinline__ void scan_block(const Ctx& C, const PV& P, int layer, int sq, int h, int d, int row0, unsigned char* smem) {
;     ...
;             for (int i = 0; i < CH; ++i) {
;                 f32x2 kk2[KT / 2], w2[KT / 2], b2[KT / 2], kd2[KT / 2], r2[KT / 2];
; #pragma unroll
;                 for (int u = 0; u < KT / 4; ++u) {
;                     kk2[2 * u] = (f32x2){nx[0][u][0], nx[0][u][1]}; kk2[2 * u + 1] = (f32x2){nx[0][u][2], nx[0][u][3]};
;                     w2[2 * u] = (f32x2){nx[1][u][0], nx[1][u][1]}; w2[2 * u + 1] = (f32x2){nx[1][u][2], nx[1][u][3]};
;                     b2[2 * u] = (f32x2){nx[2][u][0], nx[2][u][1]}; b2[2 * u + 1] = (f32x2){nx[2][u][2], nx[2][u][3]};
;                     kd2[2 * u] = (f32x2){nx[3][u][0], nx[3][u][1]}; kd2[2 * u + 1] = (f32x2){nx[3][u][2], nx[3][u][3]};
;                     r2[2 * u] = (f32x2){nx[4][u][0], nx[4][u][1]}; r2[2 * u + 1] = (f32x2){nx[4][u][2], nx[4][u][3]};
;                 }
;                 const float vv = nvv;
;                 if (i + 1 < CH) {
; #pragma unroll
;                     for (int u = 0; u < KT / 4; ++u)
; #pragma unroll
;                         for (int a5 = 0; a5 < 5; ++a5) nx[a5][u] = vp0[(i + 1) * 16 + a5 * CH * 16 + u];
;                     nvv = vbuf[(i + 1) * 64 + row];
;                 }
;                 f32x2 acc2 = s[0] * kk2[0];
; #pragma unroll
;                 for (int j = 1; j < KT / 2; ++j) acc2 = __builtin_elementwise_fma(s[j], kk2[j], acc2);
;                 float sa = acc2[0] + acc2[1];
;                 sa += dppf<0xB1>(sa); sa += dppf<0x4E>(sa); sa += dppf<0x141>(sa);
;                 if (TPR == 16) sa += dppf<0x140>(sa);
;                 sa = -sa;
;                 const f32x2 sa2 = (f32x2){sa, sa}, vv2 = (f32x2){vv, vv};
;                 f32x2 y2 = (f32x2){0.f, 0.f};
; #pragma unroll
;                 for (int j = 0; j < KT / 2; ++j) {
;                     s[j] = __builtin_elementwise_fma(s[j], w2[j], __builtin_elementwise_fma(sa2, b2[j], vv2 * kd2[j]));
;                     y2 = __builtin_elementwise_fma(s[j], r2[j], y2);
;                 }
;                 float y = y2[0] + y2[1];
;                 y += dppf<0xB1>(y); y += dppf<0x4E>(y);
;                 yv[i] = y;
;             }
;             if ((q & 3) == 0) {
; #pragma unroll
	v_add_f32_dpp v102, v102, v102 quad_perm:[1,0,3,2] row_mask:0xf bank_mask:0xf bound_ctrl:1
	v_add_f32_dpp v103, v103, v103 quad_perm:[1,0,3,2] row_mask:0xf bank_mask:0xf bound_ctrl:1
	ds_read2st64_b32 v[186:187], v201 offset0:92 offset1:93
	v_add_f32_dpp v102, v102, v102 quad_perm:[2,3,0,1] row_mask:0xf bank_mask:0xf bound_ctrl:1
	v_add_f32_dpp v103, v103, v103 quad_perm:[2,3,0,1] row_mask:0xf bank_mask:0xf bound_ctrl:1
	ds_write2st64_b32 v202, v102, v103 offset0:116 offset1:117
	ds_read2st64_b32 v[190:191], v203 offset0:92 offset1:93
	ds_read_b128 v[8:11], v200 offset:3072
	ds_read_b128 v[12:15], v200 offset:3088
	ds_read_b128 v[32:35], v200 offset:15360
	ds_read_b128 v[36:39], v200 offset:15376
	ds_read_b128 v[24:27], v200 offset:11264
	ds_read_b128 v[28:31], v200 offset:11280
	ds_read_b128 v[16:19], v200 offset:7168
	ds_read_b128 v[20:23], v200 offset:7184
	ds_read_b128 v[48:51], v200 offset:19456
	ds_read_b128 v[52:55], v200 offset:19472
	v_pk_mul_f32 v[104:105], v[0:1], v[148:149]
	v_pk_mul_f32 v[106:107], v[204:205], v[148:149]
	v_pk_fma_f32 v[104:105], v[2:3], v[150:151], v[104:105]
	v_pk_fma_f32 v[106:107], v[206:207], v[150:151], v[106:107]
	v_pk_fma_f32 v[104:105], v[4:5], v[152:153], v[104:105]
	v_pk_fma_f32 v[106:107], v[208:209], v[152:153], v[106:107]
	v_pk_fma_f32 v[104:105], v[6:7], v[154:155], v[104:105]
	v_pk_fma_f32 v[106:107], v[210:211], v[154:155], v[106:107]
	v_add_f32_e32 v108, v104, v105
	v_add_f32_e32 v110, v106, v107
	v_pk_mul_f32 v[112:113], v[172:173], v[188:189] op_sel:[0,1] op_sel_hi:[1,1]
	v_add_f32_dpp v108, v108, v108 quad_perm:[1,0,3,2] row_mask:0xf bank_mask:0xf bound_ctrl:1
	v_add_f32_dpp v110, v110, v110 quad_perm:[1,0,3,2] row_mask:0xf bank_mask:0xf bound_ctrl:1
	v_pk_mul_f32 v[120:121], v[172:173], v[192:193] op_sel:[0,1] op_sel_hi:[1,1]
	v_add_f32_dpp v108, v108, v108 quad_perm:[2,3,0,1] row_mask:0xf bank_mask:0xf bound_ctrl:1
	v_add_f32_dpp v110, v110, v110 quad_perm:[2,3,0,1] row_mask:0xf bank_mask:0xf bound_ctrl:1
	v_pk_mul_f32 v[114:115], v[174:175], v[188:189] op_sel:[0,1] op_sel_hi:[1,1]
	v_add_f32_dpp v108, v108, v108 row_half_mirror row_mask:0xf bank_mask:0xf bound_ctrl:1
	v_add_f32_dpp v110, v110, v110 row_half_mirror row_mask:0xf bank_mask:0xf bound_ctrl:1
	v_pk_mul_f32 v[122:123], v[174:175], v[192:193] op_sel:[0,1] op_sel_hi:[1,1]
	v_pk_mul_f32 v[116:117], v[176:177], v[188:189] op_sel:[0,1] op_sel_hi:[1,1]
	v_pk_mul_f32 v[124:125], v[176:177], v[192:193] op_sel:[0,1] op_sel_hi:[1,1]
	v_pk_mul_f32 v[118:119], v[178:179], v[188:189] op_sel:[0,1] op_sel_hi:[1,1]
	v_pk_mul_f32 v[126:127], v[178:179], v[192:193] op_sel:[0,1] op_sel_hi:[1,1]
	v_pk_fma_f32 v[112:113], v[108:109], v[164:165], v[112:113] op_sel_hi:[0,1,1] neg_lo:[1,0,0] neg_hi:[1,0,0]
	v_pk_fma_f32 v[120:121], v[110:111], v[164:165], v[120:121] op_sel_hi:[0,1,1] neg_lo:[1,0,0] neg_hi:[1,0,0]
	v_pk_fma_f32 v[114:115], v[108:109], v[166:167], v[114:115] op_sel_hi:[0,1,1] neg_lo:[1,0,0] neg_hi:[1,0,0]
	v_pk_fma_f32 v[122:123], v[110:111], v[166:167], v[122:123] op_sel_hi:[0,1,1] neg_lo:[1,0,0] neg_hi:[1,0,0]
	v_pk_fma_f32 v[116:117], v[108:109], v[168:169], v[116:117] op_sel_hi:[0,1,1] neg_lo:[1,0,0] neg_hi:[1,0,0]
	v_pk_fma_f32 v[124:125], v[110:111], v[168:169], v[124:125] op_sel_hi:[0,1,1] neg_lo:[1,0,0] neg_hi:[1,0,0]
	v_pk_fma_f32 v[118:119], v[108:109], v[170:171], v[118:119] op_sel_hi:[0,1,1] neg_lo:[1,0,0] neg_hi:[1,0,0]
	v_pk_fma_f32 v[126:127], v[110:111], v[170:171], v[126:127] op_sel_hi:[0,1,1] neg_lo:[1,0,0] neg_hi:[1,0,0]
	v_pk_fma_f32 v[0:1], v[0:1], v[156:157], v[112:113]
	v_pk_fma_f32 v[204:205], v[204:205], v[156:157], v[120:121]
	v_pk_fma_f32 v[2:3], v[2:3], v[158:159], v[114:115]
	v_pk_fma_f32 v[206:207], v[206:207], v[158:159], v[122:123]
	v_pk_fma_f32 v[4:5], v[4:5], v[160:161], v[116:117]
	v_pk_fma_f32 v[208:209], v[208:209], v[160:161], v[124:125]
	v_pk_fma_f32 v[6:7], v[6:7], v[162:163], v[118:119]
	v_pk_fma_f32 v[210:211], v[210:211], v[162:163], v[126:127]
	v_pk_fma_f32 v[128:129], v[0:1], v[56:57], 0 op_sel_hi:[1,1,0]
	v_pk_fma_f32 v[130:131], v[204:205], v[56:57], 0 op_sel_hi:[1,1,0]
	v_pk_fma_f32 v[128:129], v[2:3], v[58:59], v[128:129]
	v_pk_fma_f32 v[130:131], v[206:207], v[58:59], v[130:131]
	v_pk_fma_f32 v[128:129], v[4:5], v[140:141], v[128:129]
	v_pk_fma_f32 v[130:131], v[208:209], v[140:141], v[130:131]
	v_pk_fma_f32 v[128:129], v[6:7], v[142:143], v[128:129]
	v_pk_fma_f32 v[130:131], v[210:211], v[142:143], v[130:131]
	v_add_f32_e32 v102, v128, v129
	v_add_f32_e32 v103, v130, v131
	s_waitcnt lgkmcnt(0)
; template <int KT>
; __device__ __forceinline__ void scan_block(const Ctx& C, const PV& P, int layer, int sq, int h, int d, int row0, unsigned char* smem) {
;     ...
;             for (int i = 0; i < CH; ++i) {
;                 f32x2 kk2[KT / 2], w2[KT / 2], b2[KT / 2], kd2[KT / 2], r2[KT / 2];
; #pragma unroll
;                 for (int u = 0; u < KT / 4; ++u) {
;                     kk2[2 * u] = (f32x2){nx[0][u][0], nx[0][u][1]}; kk2[2 * u + 1] = (f32x2){nx[0][u][2], nx[0][u][3]};
;                     w2[2 * u] = (f32x2){nx[1][u][0], nx[1][u][1]}; w2[2 * u + 1] = (f32x2){nx[1][u][2], nx[1][u][3]};
;                     b2[2 * u] = (f32x2){nx[2][u][0], nx[2][u][1]}; b2[2 * u + 1] = (f32x2){nx[2][u][2], nx[2][u][3]};
;                     kd2[2 * u] = (f32x2){nx[3][u][0], nx[3][u][1]}; kd2[2 * u + 1] = (f32x2){nx[3][u][2], nx[3][u][3]};
;                     r2[2 * u] = (f32x2){nx[4][u][0], nx[4][u][1]}; r2[2 * u + 1] = (f32x2){nx[4][u][2], nx[4][u][3]};
;                 }
;                 const float vv = nvv;
;                 if (i + 1 < CH) {
; #pragma unroll
;                     for (int u = 0; u < KT / 4; ++u)
; #pragma unroll
;                         for (int a5 = 0; a5 < 5; ++a5) nx[a5][u] = vp0[(i + 1) * 16 + a5 * CH * 16 + u];
;                     nvv = vbuf[(i + 1) * 64 + row];
;                 }
;                 f32x2 acc2 = s[0] * kk2[0];
; #pragma unroll
;                 for (int j = 1; j < KT / 2; ++j) acc2 = __builtin_elementwise_fma(s[j], kk2[j], acc2);
;                 float sa = acc2[0] + acc2[1];
;                 sa += dppf<0xB1>(sa); sa += dppf<0x4E>(sa); sa += dppf<0x141>(sa);
;                 if (TPR == 16) sa += dppf<0x140>(sa);
;                 sa = -sa;
;                 const f32x2 sa2 = (f32x2){sa, sa}, vv2 = (f32x2){vv, vv};
;                 f32x2 y2 = (f32x2){0.f, 0.f};
; #pragma unroll
;                 for (int j = 0; j < KT / 2; ++j) {
;                     s[j] = __builtin_elementwise_fma(s[j], w2[j], __builtin_elementwise_fma(sa2, b2[j], vv2 * kd2[j]));
;                     y2 = __builtin_elementwise_fma(s[j], r2[j], y2);
;                 }
;                 float y = y2[0] + y2[1];
;                 y += dppf<0xB1>(y); y += dppf<0x4E>(y);
;                 yv[i] = y;
;             }
;             if ((q & 3) == 0) {
; #pragma unroll
	v_add_f32_dpp v102, v102, v102 quad_perm:[1,0,3,2] row_mask:0xf bank_mask:0xf bound_ctrl:1
	v_add_f32_dpp v103, v103, v103 quad_perm:[1,0,3,2] row_mask:0xf bank_mask:0xf bound_ctrl:1
	ds_read_b128 v[148:151], v200 offset:3328
	v_add_f32_dpp v102, v102, v102 quad_perm:[2,3,0,1] row_mask:0xf bank_mask:0xf bound_ctrl:1
	v_add_f32_dpp v103, v103, v103 quad_perm:[2,3,0,1] row_mask:0xf bank_mask:0xf bound_ctrl:1
	ds_write2st64_b32 v202, v102, v103 offset0:118 offset1:119
	ds_read_b128 v[152:155], v200 offset:3344
	ds_read_b128 v[172:175], v200 offset:15616
	ds_read_b128 v[176:179], v200 offset:15632
	ds_read_b128 v[164:167], v200 offset:11520
	ds_read_b128 v[168:171], v200 offset:11536
	ds_read_b128 v[156:159], v200 offset:7424
	ds_read_b128 v[160:163], v200 offset:7440
	ds_read_b128 v[56:59], v200 offset:19712
	ds_read_b128 v[140:143], v200 offset:19728
	v_pk_mul_f32 v[104:105], v[0:1], v[8:9]
	v_pk_mul_f32 v[106:107], v[204:205], v[8:9]
	v_pk_fma_f32 v[104:105], v[2:3], v[10:11], v[104:105]
	v_pk_fma_f32 v[106:107], v[206:207], v[10:11], v[106:107]
	v_pk_fma_f32 v[104:105], v[4:5], v[12:13], v[104:105]
	v_pk_fma_f32 v[106:107], v[208:209], v[12:13], v[106:107]
	v_pk_fma_f32 v[104:105], v[6:7], v[14:15], v[104:105]
	v_pk_fma_f32 v[106:107], v[210:211], v[14:15], v[106:107]
	v_add_f32_e32 v108, v104, v105
	v_add_f32_e32 v110, v106, v107
	v_pk_mul_f32 v[112:113], v[32:33], v[186:187] op_sel_hi:[1,0]
	v_add_f32_dpp v108, v108, v108 quad_perm:[1,0,3,2] row_mask:0xf bank_mask:0xf bound_ctrl:1
	v_add_f32_dpp v110, v110, v110 quad_perm:[1,0,3,2] row_mask:0xf bank_mask:0xf bound_ctrl:1
	v_pk_mul_f32 v[120:121], v[32:33], v[190:191] op_sel_hi:[1,0]
	v_add_f32_dpp v108, v108, v108 quad_perm:[2,3,0,1] row_mask:0xf bank_mask:0xf bound_ctrl:1
	v_add_f32_dpp v110, v110, v110 quad_perm:[2,3,0,1] row_mask:0xf bank_mask:0xf bound_ctrl:1
	v_pk_mul_f32 v[114:115], v[34:35], v[186:187] op_sel_hi:[1,0]
	v_add_f32_dpp v108, v108, v108 row_half_mirror row_mask:0xf bank_mask:0xf bound_ctrl:1
	v_add_f32_dpp v110, v110, v110 row_half_mirror row_mask:0xf bank_mask:0xf bound_ctrl:1
	v_pk_mul_f32 v[122:123], v[34:35], v[190:191] op_sel_hi:[1,0]
	v_pk_mul_f32 v[116:117], v[36:37], v[186:187] op_sel_hi:[1,0]
	v_pk_mul_f32 v[124:125], v[36:37], v[190:191] op_sel_hi:[1,0]
	v_pk_mul_f32 v[118:119], v[38:39], v[186:187] op_sel_hi:[1,0]
	v_pk_mul_f32 v[126:127], v[38:39], v[190:191] op_sel_hi:[1,0]
	v_pk_fma_f32 v[112:113], v[108:109], v[24:25], v[112:113] op_sel_hi:[0,1,1] neg_lo:[1,0,0] neg_hi:[1,0,0]
	v_pk_fma_f32 v[120:121], v[110:111], v[24:25], v[120:121] op_sel_hi:[0,1,1] neg_lo:[1,0,0] neg_hi:[1,0,0]
	v_pk_fma_f32 v[114:115], v[108:109], v[26:27], v[114:115] op_sel_hi:[0,1,1] neg_lo:[1,0,0] neg_hi:[1,0,0]
	v_pk_fma_f32 v[122:123], v[110:111], v[26:27], v[122:123] op_sel_hi:[0,1,1] neg_lo:[1,0,0] neg_hi:[1,0,0]
	v_pk_fma_f32 v[116:117], v[108:109], v[28:29], v[116:117] op_sel_hi:[0,1,1] neg_lo:[1,0,0] neg_hi:[1,0,0]
	v_pk_fma_f32 v[124:125], v[110:111], v[28:29], v[124:125] op_sel_hi:[0,1,1] neg_lo:[1,0,0] neg_hi:[1,0,0]
	v_pk_fma_f32 v[118:119], v[108:109], v[30:31], v[118:119] op_sel_hi:[0,1,1] neg_lo:[1,0,0] neg_hi:[1,0,0]
	v_pk_fma_f32 v[126:127], v[110:111], v[30:31], v[126:127] op_sel_hi:[0,1,1] neg_lo:[1,0,0] neg_hi:[1,0,0]
	v_pk_fma_f32 v[0:1], v[0:1], v[16:17], v[112:113]
	v_pk_fma_f32 v[204:205], v[204:205], v[16:17], v[120:121]
	v_pk_fma_f32 v[2:3], v[2:3], v[18:19], v[114:115]
	v_pk_fma_f32 v[206:207], v[206:207], v[18:19], v[122:123]
	v_pk_fma_f32 v[4:5], v[4:5], v[20:21], v[116:117]
	v_pk_fma_f32 v[208:209], v[208:209], v[20:21], v[124:125]
	v_pk_fma_f32 v[6:7], v[6:7], v[22:23], v[118:119]
	v_pk_fma_f32 v[210:211], v[210:211], v[22:23], v[126:127]
	v_pk_fma_f32 v[128:129], v[0:1], v[48:49], 0 op_sel_hi:[1,1,0]
	v_pk_fma_f32 v[130:131], v[204:205], v[48:49], 0 op_sel_hi:[1,1,0]
	v_pk_fma_f32 v[128:129], v[2:3], v[50:51], v[128:129]
	v_pk_fma_f32 v[130:131], v[206:207], v[50:51], v[130:131]
	v_pk_fma_f32 v[128:129], v[4:5], v[52:53], v[128:129]
	v_pk_fma_f32 v[130:131], v[208:209], v[52:53], v[130:131]
	v_pk_fma_f32 v[128:129], v[6:7], v[54:55], v[128:129]
	v_pk_fma_f32 v[130:131], v[210:211], v[54:55], v[130:131]
	v_add_f32_e32 v102, v128, v129
	v_add_f32_e32 v103, v130, v131
	s_waitcnt lgkmcnt(0)
; template <int KT>
; __device__ __forceinline__ void scan_block(const Ctx& C, const PV& P, int layer, int sq, int h, int d, int row0, unsigned char* smem) {
;     ...
;             for (int i = 0; i < CH; ++i) {
;                 f32x2 kk2[KT / 2], w2[KT / 2], b2[KT / 2], kd2[KT / 2], r2[KT / 2];
; #pragma unroll
;                 for (int u = 0; u < KT / 4; ++u) {
;                     kk2[2 * u] = (f32x2){nx[0][u][0], nx[0][u][1]}; kk2[2 * u + 1] = (f32x2){nx[0][u][2], nx[0][u][3]};
;                     w2[2 * u] = (f32x2){nx[1][u][0], nx[1][u][1]}; w2[2 * u + 1] = (f32x2){nx[1][u][2], nx[1][u][3]};
;                     b2[2 * u] = (f32x2){nx[2][u][0], nx[2][u][1]}; b2[2 * u + 1] = (f32x2){nx[2][u][2], nx[2][u][3]};
;                     kd2[2 * u] = (f32x2){nx[3][u][0], nx[3][u][1]}; kd2[2 * u + 1] = (f32x2){nx[3][u][2], nx[3][u][3]};
;                     r2[2 * u] = (f32x2){nx[4][u][0], nx[4][u][1]}; r2[2 * u + 1] = (f32x2){nx[4][u][2], nx[4][u][3]};
;                 }
;                 const float vv = nvv;
;                 if (i + 1 < CH) {
; #pragma unroll
;                     for (int u = 0; u < KT / 4; ++u)
; #pragma unroll
;                         for (int a5 = 0; a5 < 5; ++a5) nx[a5][u] = vp0[(i + 1) * 16 + a5 * CH * 16 + u];
;                     nvv = vbuf[(i + 1) * 64 + row];
;                 }
;                 f32x2 acc2 = s[0] * kk2[0];
; #pragma unroll
;                 for (int j = 1; j < KT / 2; ++j) acc2 = __builtin_elementwise_fma(s[j], kk2[j], acc2);
;                 float sa = acc2[0] + acc2[1];
;                 sa += dppf<0xB1>(sa); sa += dppf<0x4E>(sa); sa += dppf<0x141>(sa);
;                 if (TPR == 16) sa += dppf<0x140>(sa);
;                 sa = -sa;
;                 const f32x2 sa2 = (f32x2){sa, sa}, vv2 = (f32x2){vv, vv};
;                 f32x2 y2 = (f32x2){0.f, 0.f};
; #pragma unroll
;                 for (int j = 0; j < KT / 2; ++j) {
;                     s[j] = __builtin_elementwise_fma(s[j], w2[j], __builtin_elementwise_fma(sa2, b2[j], vv2 * kd2[j]));
;                     y2 = __builtin_elementwise_fma(s[j], r2[j], y2);
;                 }
;                 float y = y2[0] + y2[1];
;                 y += dppf<0xB1>(y); y += dppf<0x4E>(y);
;                 yv[i] = y;
;             }
;             if ((q & 3) == 0) {
; #pragma unroll
	v_add_f32_dpp v102, v102, v102 quad_perm:[1,0,3,2] row_mask:0xf bank_mask:0xf bound_ctrl:1
	v_add_f32_dpp v103, v103, v103 quad_perm:[1,0,3,2] row_mask:0xf bank_mask:0xf bound_ctrl:1
	ds_read2st64_b32 v[188:189], v201 offset0:94 offset1:95
	v_add_f32_dpp v102, v102, v102 quad_perm:[2,3,0,1] row_mask:0xf bank_mask:0xf bound_ctrl:1
	v_add_f32_dpp v103, v103, v103 quad_perm:[2,3,0,1] row_mask:0xf bank_mask:0xf bound_ctrl:1
	ds_write2st64_b32 v202, v102, v103 offset0:120 offset1:121
	ds_read2st64_b32 v[192:193], v203 offset0:94 offset1:95
	ds_read_b128 v[8:11], v200 offset:3584
	ds_read_b128 v[12:15], v200 offset:3600
	ds_read_b128 v[32:35], v200 offset:15872
	ds_read_b128 v[36:39], v200 offset:15888
	ds_read_b128 v[24:27], v200 offset:11776
	ds_read_b128 v[28:31], v200 offset:11792
	ds_read_b128 v[16:19], v200 offset:7680
	ds_read_b128 v[20:23], v200 offset:7696
	ds_read_b128 v[48:51], v200 offset:19968
	ds_read_b128 v[52:55], v200 offset:19984
	v_pk_mul_f32 v[104:105], v[0:1], v[148:149]
	v_pk_mul_f32 v[106:107], v[204:205], v[148:149]
	v_pk_fma_f32 v[104:105], v[2:3], v[150:151], v[104:105]
	v_pk_fma_f32 v[106:107], v[206:207], v[150:151], v[106:107]
	v_pk_fma_f32 v[104:105], v[4:5], v[152:153], v[104:105]
	v_pk_fma_f32 v[106:107], v[208:209], v[152:153], v[106:107]
	v_pk_fma_f32 v[104:105], v[6:7], v[154:155], v[104:105]
	v_pk_fma_f32 v[106:107], v[210:211], v[154:155], v[106:107]
	v_add_f32_e32 v108, v104, v105
	v_add_f32_e32 v110, v106, v107
	v_pk_mul_f32 v[112:113], v[172:173], v[186:187] op_sel:[0,1] op_sel_hi:[1,1]
	v_add_f32_dpp v108, v108, v108 quad_perm:[1,0,3,2] row_mask:0xf bank_mask:0xf bound_ctrl:1
	v_add_f32_dpp v110, v110, v110 quad_perm:[1,0,3,2] row_mask:0xf bank_mask:0xf bound_ctrl:1
	v_pk_mul_f32 v[120:121], v[172:173], v[190:191] op_sel:[0,1] op_sel_hi:[1,1]
	v_add_f32_dpp v108, v108, v108 quad_perm:[2,3,0,1] row_mask:0xf bank_mask:0xf bound_ctrl:1
	v_add_f32_dpp v110, v110, v110 quad_perm:[2,3,0,1] row_mask:0xf bank_mask:0xf bound_ctrl:1
	v_pk_mul_f32 v[114:115], v[174:175], v[186:187] op_sel:[0,1] op_sel_hi:[1,1]
	v_add_f32_dpp v108, v108, v108 row_half_mirror row_mask:0xf bank_mask:0xf bound_ctrl:1
	v_add_f32_dpp v110, v110, v110 row_half_mirror row_mask:0xf bank_mask:0xf bound_ctrl:1
	v_pk_mul_f32 v[122:123], v[174:175], v[190:191] op_sel:[0,1] op_sel_hi:[1,1]
	v_pk_mul_f32 v[116:117], v[176:177], v[186:187] op_sel:[0,1] op_sel_hi:[1,1]
	v_pk_mul_f32 v[124:125], v[176:177], v[190:191] op_sel:[0,1] op_sel_hi:[1,1]
	v_pk_mul_f32 v[118:119], v[178:179], v[186:187] op_sel:[0,1] op_sel_hi:[1,1]
	v_pk_mul_f32 v[126:127], v[178:179], v[190:191] op_sel:[0,1] op_sel_hi:[1,1]
	v_pk_fma_f32 v[112:113], v[108:109], v[164:165], v[112:113] op_sel_hi:[0,1,1] neg_lo:[1,0,0] neg_hi:[1,0,0]
	v_pk_fma_f32 v[120:121], v[110:111], v[164:165], v[120:121] op_sel_hi:[0,1,1] neg_lo:[1,0,0] neg_hi:[1,0,0]
	v_pk_fma_f32 v[114:115], v[108:109], v[166:167], v[114:115] op_sel_hi:[0,1,1] neg_lo:[1,0,0] neg_hi:[1,0,0]
	v_pk_fma_f32 v[122:123], v[110:111], v[166:167], v[122:123] op_sel_hi:[0,1,1] neg_lo:[1,0,0] neg_hi:[1,0,0]
	v_pk_fma_f32 v[116:117], v[108:109], v[168:169], v[116:117] op_sel_hi:[0,1,1] neg_lo:[1,0,0] neg_hi:[1,0,0]
	v_pk_fma_f32 v[124:125], v[110:111], v[168:169], v[124:125] op_sel_hi:[0,1,1] neg_lo:[1,0,0] neg_hi:[1,0,0]
	v_pk_fma_f32 v[118:119], v[108:109], v[170:171], v[118:119] op_sel_hi:[0,1,1] neg_lo:[1,0,0] neg_hi:[1,0,0]
	v_pk_fma_f32 v[126:127], v[110:111], v[170:171], v[126:127] op_sel_hi:[0,1,1] neg_lo:[1,0,0] neg_hi:[1,0,0]
	v_pk_fma_f32 v[0:1], v[0:1], v[156:157], v[112:113]
	v_pk_fma_f32 v[204:205], v[204:205], v[156:157], v[120:121]
	v_pk_fma_f32 v[2:3], v[2:3], v[158:159], v[114:115]
	v_pk_fma_f32 v[206:207], v[206:207], v[158:159], v[122:123]
	v_pk_fma_f32 v[4:5], v[4:5], v[160:161], v[116:117]
	v_pk_fma_f32 v[208:209], v[208:209], v[160:161], v[124:125]
	v_pk_fma_f32 v[6:7], v[6:7], v[162:163], v[118:119]
	v_pk_fma_f32 v[210:211], v[210:211], v[162:163], v[126:127]
	v_pk_fma_f32 v[128:129], v[0:1], v[56:57], 0 op_sel_hi:[1,1,0]
	v_pk_fma_f32 v[130:131], v[204:205], v[56:57], 0 op_sel_hi:[1,1,0]
	v_pk_fma_f32 v[128:129], v[2:3], v[58:59], v[128:129]
	v_pk_fma_f32 v[130:131], v[206:207], v[58:59], v[130:131]
	v_pk_fma_f32 v[128:129], v[4:5], v[140:141], v[128:129]
	v_pk_fma_f32 v[130:131], v[208:209], v[140:141], v[130:131]
	v_pk_fma_f32 v[128:129], v[6:7], v[142:143], v[128:129]
	v_pk_fma_f32 v[130:131], v[210:211], v[142:143], v[130:131]
	v_add_f32_e32 v102, v128, v129
	v_add_f32_e32 v103, v130, v131
	s_waitcnt lgkmcnt(0)
; template <int KT>
; __device__ __forceinline__ void scan_block(const Ctx& C, const PV& P, int layer, int sq, int h, int d, int row0, unsigned char* smem) {
;     ...
;             for (int i = 0; i < CH; ++i) {
;                 f32x2 kk2[KT / 2], w2[KT / 2], b2[KT / 2], kd2[KT / 2], r2[KT / 2];
; #pragma unroll
;                 for (int u = 0; u < KT / 4; ++u) {
;                     kk2[2 * u] = (f32x2){nx[0][u][0], nx[0][u][1]}; kk2[2 * u + 1] = (f32x2){nx[0][u][2], nx[0][u][3]};
;                     w2[2 * u] = (f32x2){nx[1][u][0], nx[1][u][1]}; w2[2 * u + 1] = (f32x2){nx[1][u][2], nx[1][u][3]};
;                     b2[2 * u] = (f32x2){nx[2][u][0], nx[2][u][1]}; b2[2 * u + 1] = (f32x2){nx[2][u][2], nx[2][u][3]};
;                     kd2[2 * u] = (f32x2){nx[3][u][0], nx[3][u][1]}; kd2[2 * u + 1] = (f32x2){nx[3][u][2], nx[3][u][3]};
;                     r2[2 * u] = (f32x2){nx[4][u][0], nx[4][u][1]}; r2[2 * u + 1] = (f32x2){nx[4][u][2], nx[4][u][3]};
;                 }
;                 const float vv = nvv;
;                 if (i + 1 < CH) {
; #pragma unroll
;                     for (int u = 0; u < KT / 4; ++u)
; #pragma unroll
;                         for (int a5 = 0; a5 < 5; ++a5) nx[a5][u] = vp0[(i + 1) * 16 + a5 * CH * 16 + u];
;                     nvv = vbuf[(i + 1) * 64 + row];
;                 }
;                 f32x2 acc2 = s[0] * kk2[0];
; #pragma unroll
;                 for (int j = 1; j < KT / 2; ++j) acc2 = __builtin_elementwise_fma(s[j], kk2[j], acc2);
;                 float sa = acc2[0] + acc2[1];
;                 sa += dppf<0xB1>(sa); sa += dppf<0x4E>(sa); sa += dppf<0x141>(sa);
;                 if (TPR == 16) sa += dppf<0x140>(sa);
;                 sa = -sa;
;                 const f32x2 sa2 = (f32x2){sa, sa}, vv2 = (f32x2){vv, vv};
;                 f32x2 y2 = (f32x2){0.f, 0.f};
; #pragma unroll
;                 for (int j = 0; j < KT / 2; ++j) {
;                     s[j] = __builtin_elementwise_fma(s[j], w2[j], __builtin_elementwise_fma(sa2, b2[j], vv2 * kd2[j]));
;                     y2 = __builtin_elementwise_fma(s[j], r2[j], y2);
;                 }
;                 float y = y2[0] + y2[1];
;                 y += dppf<0xB1>(y); y += dppf<0x4E>(y);
;                 yv[i] = y;
;             }
;             if ((q & 3) == 0) {
; #pragma unroll
	v_add_f32_dpp v102, v102, v102 quad_perm:[1,0,3,2] row_mask:0xf bank_mask:0xf bound_ctrl:1
	v_add_f32_dpp v103, v103, v103 quad_perm:[1,0,3,2] row_mask:0xf bank_mask:0xf bound_ctrl:1
	ds_read_b128 v[148:151], v200 offset:3840
	v_add_f32_dpp v102, v102, v102 quad_perm:[2,3,0,1] row_mask:0xf bank_mask:0xf bound_ctrl:1
	v_add_f32_dpp v103, v103, v103 quad_perm:[2,3,0,1] row_mask:0xf bank_mask:0xf bound_ctrl:1
	ds_write2st64_b32 v202, v102, v103 offset0:122 offset1:123
	ds_read_b128 v[152:155], v200 offset:3856
	ds_read_b128 v[172:175], v200 offset:16128
	ds_read_b128 v[176:179], v200 offset:16144
	ds_read_b128 v[164:167], v200 offset:12032
	ds_read_b128 v[168:171], v200 offset:12048
	ds_read_b128 v[156:159], v200 offset:7936
	ds_read_b128 v[160:163], v200 offset:7952
	ds_read_b128 v[56:59], v200 offset:20224
	ds_read_b128 v[140:143], v200 offset:20240
	v_pk_mul_f32 v[104:105], v[0:1], v[8:9]
	v_pk_mul_f32 v[106:107], v[204:205], v[8:9]
	v_pk_fma_f32 v[104:105], v[2:3], v[10:11], v[104:105]
	v_pk_fma_f32 v[106:107], v[206:207], v[10:11], v[106:107]
	v_pk_fma_f32 v[104:105], v[4:5], v[12:13], v[104:105]
	v_pk_fma_f32 v[106:107], v[208:209], v[12:13], v[106:107]
	v_pk_fma_f32 v[104:105], v[6:7], v[14:15], v[104:105]
	v_pk_fma_f32 v[106:107], v[210:211], v[14:15], v[106:107]
	v_add_f32_e32 v108, v104, v105
	v_add_f32_e32 v110, v106, v107
	v_pk_mul_f32 v[112:113], v[32:33], v[188:189] op_sel_hi:[1,0]
	v_add_f32_dpp v108, v108, v108 quad_perm:[1,0,3,2] row_mask:0xf bank_mask:0xf bound_ctrl:1
	v_add_f32_dpp v110, v110, v110 quad_perm:[1,0,3,2] row_mask:0xf bank_mask:0xf bound_ctrl:1
	v_pk_mul_f32 v[120:121], v[32:33], v[192:193] op_sel_hi:[1,0]
	v_add_f32_dpp v108, v108, v108 quad_perm:[2,3,0,1] row_mask:0xf bank_mask:0xf bound_ctrl:1
	v_add_f32_dpp v110, v110, v110 quad_perm:[2,3,0,1] row_mask:0xf bank_mask:0xf bound_ctrl:1
	v_pk_mul_f32 v[114:115], v[34:35], v[188:189] op_sel_hi:[1,0]
	v_add_f32_dpp v108, v108, v108 row_half_mirror row_mask:0xf bank_mask:0xf bound_ctrl:1
	v_add_f32_dpp v110, v110, v110 row_half_mirror row_mask:0xf bank_mask:0xf bound_ctrl:1
	v_pk_mul_f32 v[122:123], v[34:35], v[192:193] op_sel_hi:[1,0]
	v_pk_mul_f32 v[116:117], v[36:37], v[188:189] op_sel_hi:[1,0]
	v_pk_mul_f32 v[124:125], v[36:37], v[192:193] op_sel_hi:[1,0]
	v_pk_mul_f32 v[118:119], v[38:39], v[188:189] op_sel_hi:[1,0]
	v_pk_mul_f32 v[126:127], v[38:39], v[192:193] op_sel_hi:[1,0]
	v_pk_fma_f32 v[112:113], v[108:109], v[24:25], v[112:113] op_sel_hi:[0,1,1] neg_lo:[1,0,0] neg_hi:[1,0,0]
	v_pk_fma_f32 v[120:121], v[110:111], v[24:25], v[120:121] op_sel_hi:[0,1,1] neg_lo:[1,0,0] neg_hi:[1,0,0]
	v_pk_fma_f32 v[114:115], v[108:109], v[26:27], v[114:115] op_sel_hi:[0,1,1] neg_lo:[1,0,0] neg_hi:[1,0,0]
	v_pk_fma_f32 v[122:123], v[110:111], v[26:27], v[122:123] op_sel_hi:[0,1,1] neg_lo:[1,0,0] neg_hi:[1,0,0]
	v_pk_fma_f32 v[116:117], v[108:109], v[28:29], v[116:117] op_sel_hi:[0,1,1] neg_lo:[1,0,0] neg_hi:[1,0,0]
	v_pk_fma_f32 v[124:125], v[110:111], v[28:29], v[124:125] op_sel_hi:[0,1,1] neg_lo:[1,0,0] neg_hi:[1,0,0]
	v_pk_fma_f32 v[118:119], v[108:109], v[30:31], v[118:119] op_sel_hi:[0,1,1] neg_lo:[1,0,0] neg_hi:[1,0,0]
	v_pk_fma_f32 v[126:127], v[110:111], v[30:31], v[126:127] op_sel_hi:[0,1,1] neg_lo:[1,0,0] neg_hi:[1,0,0]
	v_pk_fma_f32 v[0:1], v[0:1], v[16:17], v[112:113]
	v_pk_fma_f32 v[204:205], v[204:205], v[16:17], v[120:121]
	v_pk_fma_f32 v[2:3], v[2:3], v[18:19], v[114:115]
	v_pk_fma_f32 v[206:207], v[206:207], v[18:19], v[122:123]
	v_pk_fma_f32 v[4:5], v[4:5], v[20:21], v[116:117]
	v_pk_fma_f32 v[208:209], v[208:209], v[20:21], v[124:125]
	v_pk_fma_f32 v[6:7], v[6:7], v[22:23], v[118:119]
	v_pk_fma_f32 v[210:211], v[210:211], v[22:23], v[126:127]
	v_pk_fma_f32 v[128:129], v[0:1], v[48:49], 0 op_sel_hi:[1,1,0]
	v_pk_fma_f32 v[130:131], v[204:205], v[48:49], 0 op_sel_hi:[1,1,0]
	v_pk_fma_f32 v[128:129], v[2:3], v[50:51], v[128:129]
	v_pk_fma_f32 v[130:131], v[206:207], v[50:51], v[130:131]
	v_pk_fma_f32 v[128:129], v[4:5], v[52:53], v[128:129]
	v_pk_fma_f32 v[130:131], v[208:209], v[52:53], v[130:131]
	v_pk_fma_f32 v[128:129], v[6:7], v[54:55], v[128:129]
	v_pk_fma_f32 v[130:131], v[210:211], v[54:55], v[130:131]
	v_add_f32_e32 v102, v128, v129
	v_add_f32_e32 v103, v130, v131
	s_waitcnt lgkmcnt(0)
; template <int KT>
; __device__ __forceinline__ void scan_block(const Ctx& C, const PV& P, int layer, int sq, int h, int d, int row0, unsigned char* smem) {
;     ...
;             for (int i = 0; i < CH; ++i) {
;                 f32x2 kk2[KT / 2], w2[KT / 2], b2[KT / 2], kd2[KT / 2], r2[KT / 2];
; #pragma unroll
;                 for (int u = 0; u < KT / 4; ++u) {
;                     kk2[2 * u] = (f32x2){nx[0][u][0], nx[0][u][1]}; kk2[2 * u + 1] = (f32x2){nx[0][u][2], nx[0][u][3]};
;                     w2[2 * u] = (f32x2){nx[1][u][0], nx[1][u][1]}; w2[2 * u + 1] = (f32x2){nx[1][u][2], nx[1][u][3]};
;                     b2[2 * u] = (f32x2){nx[2][u][0], nx[2][u][1]}; b2[2 * u + 1] = (f32x2){nx[2][u][2], nx[2][u][3]};
;                     kd2[2 * u] = (f32x2){nx[3][u][0], nx[3][u][1]}; kd2[2 * u + 1] = (f32x2){nx[3][u][2], nx[3][u][3]};
;                     r2[2 * u] = (f32x2){nx[4][u][0], nx[4][u][1]}; r2[2 * u + 1] = (f32x2){nx[4][u][2], nx[4][u][3]};
;                 }
;                 const float vv = nvv;
;                 if (i + 1 < CH) {
; #pragma unroll
;                     for (int u = 0; u < KT / 4; ++u)
; #pragma unroll
;                         for (int a5 = 0; a5 < 5; ++a5) nx[a5][u] = vp0[(i + 1) * 16 + a5 * CH * 16 + u];
;                     nvv = vbuf[(i + 1) * 64 + row];
;                 }
;                 f32x2 acc2 = s[0] * kk2[0];
; #pragma unroll
;                 for (int j = 1; j < KT / 2; ++j) acc2 = __builtin_elementwise_fma(s[j], kk2[j], acc2);
;                 float sa = acc2[0] + acc2[1];
;                 sa += dppf<0xB1>(sa); sa += dppf<0x4E>(sa); sa += dppf<0x141>(sa);
;                 if (TPR == 16) sa += dppf<0x140>(sa);
;                 sa = -sa;
;                 const f32x2 sa2 = (f32x2){sa, sa}, vv2 = (f32x2){vv, vv};
;                 f32x2 y2 = (f32x2){0.f, 0.f};
; #pragma unroll
;                 for (int j = 0; j < KT / 2; ++j) {
;                     s[j] = __builtin_elementwise_fma(s[j], w2[j], __builtin_elementwise_fma(sa2, b2[j], vv2 * kd2[j]));
;                     y2 = __builtin_elementwise_fma(s[j], r2[j], y2);
;                 }
;                 float y = y2[0] + y2[1];
;                 y += dppf<0xB1>(y); y += dppf<0x4E>(y);
;                 yv[i] = y;
;             }
;             if ((q & 3) == 0) {
; #pragma unroll
	v_add_f32_dpp v102, v102, v102 quad_perm:[1,0,3,2] row_mask:0xf bank_mask:0xf bound_ctrl:1
	v_add_f32_dpp v103, v103, v103 quad_perm:[1,0,3,2] row_mask:0xf bank_mask:0xf bound_ctrl:1
	s_nop 0
	v_add_f32_dpp v102, v102, v102 quad_perm:[2,3,0,1] row_mask:0xf bank_mask:0xf bound_ctrl:1
	v_add_f32_dpp v103, v103, v103 quad_perm:[2,3,0,1] row_mask:0xf bank_mask:0xf bound_ctrl:1
	ds_write2st64_b32 v202, v102, v103 offset0:124 offset1:125
	v_pk_mul_f32 v[104:105], v[0:1], v[148:149]
	v_pk_mul_f32 v[106:107], v[204:205], v[148:149]
	v_pk_fma_f32 v[104:105], v[2:3], v[150:151], v[104:105]
	v_pk_fma_f32 v[106:107], v[206:207], v[150:151], v[106:107]
	v_pk_fma_f32 v[104:105], v[4:5], v[152:153], v[104:105]
	v_pk_fma_f32 v[106:107], v[208:209], v[152:153], v[106:107]
	v_pk_fma_f32 v[104:105], v[6:7], v[154:155], v[104:105]
	v_pk_fma_f32 v[106:107], v[210:211], v[154:155], v[106:107]
	v_add_f32_e32 v108, v104, v105
	v_add_f32_e32 v110, v106, v107
	v_pk_mul_f32 v[112:113], v[172:173], v[188:189] op_sel:[0,1] op_sel_hi:[1,1]
	v_add_f32_dpp v108, v108, v108 quad_perm:[1,0,3,2] row_mask:0xf bank_mask:0xf bound_ctrl:1
	v_add_f32_dpp v110, v110, v110 quad_perm:[1,0,3,2] row_mask:0xf bank_mask:0xf bound_ctrl:1
	v_pk_mul_f32 v[120:121], v[172:173], v[192:193] op_sel:[0,1] op_sel_hi:[1,1]
	v_add_f32_dpp v108, v108, v108 quad_perm:[2,3,0,1] row_mask:0xf bank_mask:0xf bound_ctrl:1
	v_add_f32_dpp v110, v110, v110 quad_perm:[2,3,0,1] row_mask:0xf bank_mask:0xf bound_ctrl:1
	v_pk_mul_f32 v[114:115], v[174:175], v[188:189] op_sel:[0,1] op_sel_hi:[1,1]
	v_add_f32_dpp v108, v108, v108 row_half_mirror row_mask:0xf bank_mask:0xf bound_ctrl:1
	v_add_f32_dpp v110, v110, v110 row_half_mirror row_mask:0xf bank_mask:0xf bound_ctrl:1
	v_pk_mul_f32 v[122:123], v[174:175], v[192:193] op_sel:[0,1] op_sel_hi:[1,1]
	v_pk_mul_f32 v[116:117], v[176:177], v[188:189] op_sel:[0,1] op_sel_hi:[1,1]
	v_pk_mul_f32 v[124:125], v[176:177], v[192:193] op_sel:[0,1] op_sel_hi:[1,1]
	v_pk_mul_f32 v[118:119], v[178:179], v[188:189] op_sel:[0,1] op_sel_hi:[1,1]
	v_pk_mul_f32 v[126:127], v[178:179], v[192:193] op_sel:[0,1] op_sel_hi:[1,1]
	v_pk_fma_f32 v[112:113], v[108:109], v[164:165], v[112:113] op_sel_hi:[0,1,1] neg_lo:[1,0,0] neg_hi:[1,0,0]
	v_pk_fma_f32 v[120:121], v[110:111], v[164:165], v[120:121] op_sel_hi:[0,1,1] neg_lo:[1,0,0] neg_hi:[1,0,0]
	v_pk_fma_f32 v[114:115], v[108:109], v[166:167], v[114:115] op_sel_hi:[0,1,1] neg_lo:[1,0,0] neg_hi:[1,0,0]
	v_pk_fma_f32 v[122:123], v[110:111], v[166:167], v[122:123] op_sel_hi:[0,1,1] neg_lo:[1,0,0] neg_hi:[1,0,0]
	v_pk_fma_f32 v[116:117], v[108:109], v[168:169], v[116:117] op_sel_hi:[0,1,1] neg_lo:[1,0,0] neg_hi:[1,0,0]
	v_pk_fma_f32 v[124:125], v[110:111], v[168:169], v[124:125] op_sel_hi:[0,1,1] neg_lo:[1,0,0] neg_hi:[1,0,0]
	v_pk_fma_f32 v[118:119], v[108:109], v[170:171], v[118:119] op_sel_hi:[0,1,1] neg_lo:[1,0,0] neg_hi:[1,0,0]
	v_pk_fma_f32 v[126:127], v[110:111], v[170:171], v[126:127] op_sel_hi:[0,1,1] neg_lo:[1,0,0] neg_hi:[1,0,0]
	v_pk_fma_f32 v[0:1], v[0:1], v[156:157], v[112:113]
	v_pk_fma_f32 v[204:205], v[204:205], v[156:157], v[120:121]
	v_pk_fma_f32 v[2:3], v[2:3], v[158:159], v[114:115]
	v_pk_fma_f32 v[206:207], v[206:207], v[158:159], v[122:123]
	v_pk_fma_f32 v[4:5], v[4:5], v[160:161], v[116:117]
	v_pk_fma_f32 v[208:209], v[208:209], v[160:161], v[124:125]
	v_pk_fma_f32 v[6:7], v[6:7], v[162:163], v[118:119]
	v_pk_fma_f32 v[210:211], v[210:211], v[162:163], v[126:127]
	v_pk_fma_f32 v[128:129], v[0:1], v[56:57], 0 op_sel_hi:[1,1,0]
	v_pk_fma_f32 v[130:131], v[204:205], v[56:57], 0 op_sel_hi:[1,1,0]
	v_pk_fma_f32 v[128:129], v[2:3], v[58:59], v[128:129]
	v_pk_fma_f32 v[130:131], v[206:207], v[58:59], v[130:131]
	v_pk_fma_f32 v[128:129], v[4:5], v[140:141], v[128:129]
	v_pk_fma_f32 v[130:131], v[208:209], v[140:141], v[130:131]
	v_pk_fma_f32 v[128:129], v[6:7], v[142:143], v[128:129]
	v_pk_fma_f32 v[130:131], v[210:211], v[142:143], v[130:131]
	v_add_f32_e32 v102, v128, v129
	v_add_f32_e32 v103, v130, v131
	s_nop 0
	v_add_f32_dpp v102, v102, v102 quad_perm:[1,0,3,2] row_mask:0xf bank_mask:0xf bound_ctrl:1
	v_add_f32_dpp v103, v103, v103 quad_perm:[1,0,3,2] row_mask:0xf bank_mask:0xf bound_ctrl:1
	s_nop 0
	v_add_f32_dpp v102, v102, v102 quad_perm:[2,3,0,1] row_mask:0xf bank_mask:0xf bound_ctrl:1
	v_add_f32_dpp v103, v103, v103 quad_perm:[2,3,0,1] row_mask:0xf bank_mask:0xf bound_ctrl:1
	ds_write2st64_b32 v202, v102, v103 offset0:126 offset1:127
